# CB phase: conv-weight LDS fill loads issued together with a single wait (was two serialized load-wait-store trips behind the 16 raw row loads)
# baseline (speedup 1.0000x reference)
; DI float silu(float x) { return x * __builtin_amdgcn_rcpf(1.f + __expf(-x)); }
; DI u32x4 pack8(const float (&f)[8]) { u32x4 r; r[0] = pk2(f[0], f[1]); r[1] = pk2(f[2], f[3]); r[2] = pk2(f[4], f[5]); r[3] = pk2(f[6], f[7]); return r; }
; #define LDS_BARRIER() do { asm volatile("s_waitcnt lgkmcnt(0)" ::: "memory"); __builtin_amdgcn_s_barrier(); asm volatile("" ::: "memory"); } while (0)
; DI void ssd_cb_phase(const bf16_t* P, bf16_t* BT, bf16_t* Cc, bf16_t* CB, const float* dt, float* acs,
;                      const float* cw, const float* cb, const float* A_log, char* lds) {
;     ...
;     for (int q = tid; q < 1280; q += 512) { const int which = q / 640, r = q % 640, kk = r >> 7, col = 2048 + which * 512 + g * 128 + (r & 127); sW[q] = (kk < 4) ? cw[kk * 3072 + col] : cb[col]; }
;     LDS_BARRIER();
; #pragma unroll
;     for (int j = 0; j < 4; ++j) {
;       const int q = tid + 512 * j, l = q & 127, cch = q >> 7;
;       float v[8];
;       { const f32x4 b0 = *(const f32x4*)(sW + 512 + cch * 8), b1 = *(const f32x4*)(sW + 512 + cch * 8 + 4);
;         v[0] = b0[0]; v[1] = b0[1]; v[2] = b0[2]; v[3] = b0[3]; v[4] = b1[0]; v[5] = b1[1]; v[6] = b1[2]; v[7] = b1[3]; }
; #pragma unroll
;       for (int kk = 0; kk < 4; ++kk) {
;         float f[8]; unpack8(raw[j][kk], f);
;         const float ok = (tin0 + l - 3 + kk >= 0) ? 1.f : 0.f;
;         const f32x4 w0 = *(const f32x4*)(sW + kk * 128 + cch * 8) * ok, w1 = *(const f32x4*)(sW + kk * 128 + cch * 8 + 4) * ok;
;         v[0] += w0[0] * f[0]; v[1] += w0[1] * f[1]; v[2] += w0[2] * f[2]; v[3] += w0[3] * f[3];
;         v[4] += w1[0] * f[4]; v[5] += w1[1] * f[5]; v[6] += w1[2] * f[6]; v[7] += w1[3] * f[7];
;       }
; #pragma unroll
;       for (int e = 0; e < 8; ++e) v[e] = silu(v[e]);
;       const u32x4 pk = pack8(v);
;       *(u32x4*)(sB + swz128(l, cch)) = pk;
; #pragma unroll
;       for (int e = 0; e < 8; ++e) BTi[(cch * 8 + e) * 128 + l] = (bf16_t)(pk[e >> 1] >> (16 * (e & 1)));
.LBB0_1126:
	s_or_b64 exec, exec, s[60:61]
	s_waitcnt vmcnt(0)
	ds_write_b32 v242, v240
	ds_write_b32 v243, v241
	s_and_saveexec_b64 s[0:1], s[56:57]
	ds_write_b32 v245, v244
	s_or_b64 exec, exec, s[0:1]
	s_waitcnt lgkmcnt(0)
	s_barrier
	ds_read_b128 v[164:167], v120
	ds_read_b128 v[168:171], v119
	ds_read_b128 v[172:175], v119 offset:16
	ds_read_b128 v[176:179], v120 offset:16
	v_cmp_lt_u32_e64 s[0:1], 2, v114
	s_ashr_i32 s41, s40, 31
	v_readlane_b32 s4, v253, 16
	v_cndmask_b32_e64 v118, 0, 1.0, s[0:1]
	s_waitcnt lgkmcnt(3)
	v_pk_mul_f32 v[112:113], v[118:119], v[166:167] op_sel_hi:[0,1]
	v_pk_mul_f32 v[180:181], v[118:119], v[164:165] op_sel_hi:[0,1]
	ds_read_b128 v[164:167], v120 offset:512
	s_waitcnt lgkmcnt(1)
	v_pk_mul_f32 v[182:183], v[118:119], v[178:179] op_sel_hi:[0,1]
	v_pk_mul_f32 v[184:185], v[118:119], v[176:177] op_sel_hi:[0,1]
	ds_read_b128 v[176:179], v120 offset:528
	v_cmp_lt_u32_e64 s[0:1], 1, v114
	s_lshl_b64 s[68:69], s[40:41], 15
	v_readlane_b32 s16, v253, 28
	v_cndmask_b32_e64 v116, 0, 1.0, s[0:1]
	s_waitcnt lgkmcnt(1)
	v_pk_mul_f32 v[186:187], v[116:117], v[166:167] op_sel_hi:[0,1]
	v_pk_mul_f32 v[188:189], v[116:117], v[164:165] op_sel_hi:[0,1]
	ds_read_b128 v[164:167], v120 offset:1024
	s_waitcnt lgkmcnt(1)
	v_pk_mul_f32 v[190:191], v[116:117], v[178:179] op_sel_hi:[0,1]
	v_pk_mul_f32 v[192:193], v[116:117], v[176:177] op_sel_hi:[0,1]
	ds_read_b128 v[176:179], v120 offset:1040
	v_cmp_eq_u32_e64 s[0:1], 0, v114
	v_readlane_b32 s17, v253, 29
	s_add_u32 s64, s16, s68
	v_cndmask_b32_e64 v114, 1.0, 0, s[0:1]
	s_waitcnt lgkmcnt(1)
	v_pk_mul_f32 v[194:195], v[114:115], v[166:167] op_sel_hi:[0,1]
	v_pk_mul_f32 v[196:197], v[114:115], v[164:165] op_sel_hi:[0,1]
	ds_read_b128 v[164:167], v120 offset:1536
	s_waitcnt lgkmcnt(1)
	v_pk_mul_f32 v[198:199], v[114:115], v[178:179] op_sel_hi:[0,1]
	s_waitcnt vmcnt(15)
	v_lshlrev_b32_e32 v178, 16, v38
	v_and_b32_e32 v179, 0xffff0000, v38
	v_pk_fma_f32 v[168:169], v[180:181], v[178:179], v[168:169]
	s_waitcnt vmcnt(14)
	v_lshlrev_b32_e32 v178, 16, v34
	v_and_b32_e32 v179, 0xffff0000, v34
	v_pk_fma_f32 v[168:169], v[188:189], v[178:179], v[168:169]
	s_waitcnt vmcnt(13)
	v_lshlrev_b32_e32 v178, 16, v46
	v_and_b32_e32 v179, 0xffff0000, v46
	v_pk_fma_f32 v[168:169], v[196:197], v[178:179], v[168:169]
	s_waitcnt vmcnt(12)
	v_lshlrev_b32_e32 v188, 16, v42
	v_and_b32_e32 v189, 0xffff0000, v42
	ds_read_b128 v[178:181], v120 offset:1552
	s_waitcnt lgkmcnt(1)
	v_pk_fma_f32 v[164:165], v[164:165], v[188:189], v[168:169]
	v_pk_mul_f32 v[168:169], v[114:115], v[176:177] op_sel_hi:[0,1]
	v_mul_f32_e32 v38, 0xbfb8aa3b, v165
	v_exp_f32_e32 v38, v38
	v_lshlrev_b32_e32 v46, 16, v47
	v_and_b32_e32 v47, 0xffff0000, v47
	v_lshlrev_b32_e32 v42, 16, v43
	v_add_f32_e32 v176, 1.0, v38
	v_lshlrev_b32_e32 v38, 16, v39
	v_and_b32_e32 v39, 0xffff0000, v39
	v_pk_fma_f32 v[38:39], v[112:113], v[38:39], v[170:171]
	v_lshlrev_b32_e32 v112, 16, v35
	v_and_b32_e32 v113, 0xffff0000, v35
	v_pk_fma_f32 v[38:39], v[186:187], v[112:113], v[38:39]
	v_lshlrev_b32_e32 v112, 16, v36
	v_pk_fma_f32 v[38:39], v[194:195], v[46:47], v[38:39]
	v_lshlrev_b32_e32 v46, 16, v40
	v_and_b32_e32 v47, 0xffff0000, v40
	v_pk_fma_f32 v[46:47], v[184:185], v[46:47], v[172:173]
	v_and_b32_e32 v113, 0xffff0000, v36
	v_pk_fma_f32 v[46:47], v[192:193], v[112:113], v[46:47]
	v_lshlrev_b32_e32 v112, 16, v48
	v_and_b32_e32 v113, 0xffff0000, v48
	v_pk_fma_f32 v[46:47], v[168:169], v[112:113], v[46:47]
	v_lshlrev_b32_e32 v112, 16, v44
	v_and_b32_e32 v113, 0xffff0000, v44
	s_waitcnt lgkmcnt(0)
	v_pk_fma_f32 v[46:47], v[178:179], v[112:113], v[46:47]
	v_and_b32_e32 v43, 0xffff0000, v43
	v_mul_f32_e32 v40, 0xbfb8aa3b, v47
	v_exp_f32_e32 v40, v40
	v_pk_fma_f32 v[38:39], v[166:167], v[42:43], v[38:39]
	v_lshlrev_b32_e32 v112, 16, v37
	v_and_b32_e32 v113, 0xffff0000, v37
	v_add_f32_e32 v166, 1.0, v40
	v_lshlrev_b32_e32 v40, 16, v41
	v_and_b32_e32 v41, 0xffff0000, v41
	v_pk_fma_f32 v[40:41], v[182:183], v[40:41], v[174:175]
	v_lshlrev_b32_e32 v48, 16, v49
	v_pk_fma_f32 v[40:41], v[190:191], v[112:113], v[40:41]
	v_and_b32_e32 v49, 0xffff0000, v49
	v_pk_fma_f32 v[40:41], v[198:199], v[48:49], v[40:41]
	v_lshlrev_b32_e32 v44, 16, v45
	v_and_b32_e32 v45, 0xffff0000, v45
	v_pk_fma_f32 v[40:41], v[180:181], v[44:45], v[40:41]
	v_mul_f32_e32 v35, 0xbfb8aa3b, v38
	v_mul_f32_e32 v37, 0xbfb8aa3b, v40
	v_mul_f32_e32 v34, 0xbfb8aa3b, v164
	v_exp_f32_e32 v42, v35
	v_mul_f32_e32 v35, 0xbfb8aa3b, v39
	v_mul_f32_e32 v36, 0xbfb8aa3b, v46
	v_exp_f32_e32 v44, v37
	v_mul_f32_e32 v37, 0xbfb8aa3b, v41
	v_exp_f32_e32 v34, v34
	v_exp_f32_e32 v43, v35
	v_exp_f32_e32 v36, v36
	v_exp_f32_e32 v45, v37
	v_add_f32_e32 v34, 1.0, v34
	v_add_f32_e32 v42, 1.0, v42
	v_add_f32_e32 v43, 1.0, v43
	v_add_f32_e32 v36, 1.0, v36
	v_add_f32_e32 v44, 1.0, v44
	v_add_f32_e32 v45, 1.0, v45
	v_rcp_f32_e32 v34, v34
	v_rcp_f32_e32 v35, v176
	v_rcp_f32_e32 v42, v42
	v_rcp_f32_e32 v43, v43
	v_rcp_f32_e32 v36, v36
	v_rcp_f32_e32 v37, v166
	v_rcp_f32_e32 v44, v44
	v_rcp_f32_e32 v45, v45
	s_addc_u32 s65, s17, s69
	v_pk_mul_f32 v[34:35], v[164:165], v[34:35]
	v_pk_mul_f32 v[38:39], v[38:39], v[42:43]
	v_pk_mul_f32 v[36:37], v[46:47], v[36:37]
	v_pk_mul_f32 v[40:41], v[40:41], v[44:45]
	v_add_u32_e32 v164, s78, v76
	v_cvt_pk_bf16_f32 v34, v34, v35
	v_cvt_pk_bf16_f32 v35, v38, v39
	v_cvt_pk_bf16_f32 v36, v36, v37
	v_cvt_pk_bf16_f32 v37, v40, v41
	v_lshl_add_u64 v[38:39], v[84:85], 1, s[64:65]
	v_cmp_gt_i32_e64 s[0:1], 3, v164
	v_readlane_b32 s18, v253, 30
	v_readlane_b32 s19, v253, 31
	ds_write_b128 v156, v[34:37]
	global_store_short v[38:39], v34, off
	global_store_short_d16_hi v[38:39], v34, off offset:256
; DI float silu(float x) { return x * __builtin_amdgcn_rcpf(1.f + __expf(-x)); }
; DI u32x4 pack8(const float (&f)[8]) { u32x4 r; r[0] = pk2(f[0], f[1]); r[1] = pk2(f[2], f[3]); r[2] = pk2(f[4], f[5]); r[3] = pk2(f[6], f[7]); return r; }
; DI void ssd_cb_phase(const bf16_t* P, bf16_t* BT, bf16_t* Cc, bf16_t* CB, const float* dt, float* acs,
;                      const float* cw, const float* cb, const float* A_log, char* lds) {
;     ...
;       const int q = tid + 512 * j, l = q & 127, cch = q >> 7;
;       float v[8];
;       { const f32x4 b0 = *(const f32x4*)(sW + 512 + cch * 8), b1 = *(const f32x4*)(sW + 512 + cch * 8 + 4);
;         v[0] = b0[0]; v[1] = b0[1]; v[2] = b0[2]; v[3] = b0[3]; v[4] = b1[0]; v[5] = b1[1]; v[6] = b1[2]; v[7] = b1[3]; }
; #pragma unroll
;       for (int kk = 0; kk < 4; ++kk) {
;         float f[8]; unpack8(raw[j][kk], f);
;         const float ok = (tin0 + l - 3 + kk >= 0) ? 1.f : 0.f;
;         const f32x4 w0 = *(const f32x4*)(sW + kk * 128 + cch * 8) * ok, w1 = *(const f32x4*)(sW + kk * 128 + cch * 8 + 4) * ok;
;         v[0] += w0[0] * f[0]; v[1] += w0[1] * f[1]; v[2] += w0[2] * f[2]; v[3] += w0[3] * f[3];
;         v[4] += w1[0] * f[4]; v[5] += w1[1] * f[5]; v[6] += w1[2] * f[6]; v[7] += w1[3] * f[7];
;       }
; #pragma unroll
;       for (int e = 0; e < 8; ++e) v[e] = silu(v[e]);
;       const u32x4 pk = pack8(v);
;       *(u32x4*)(sB + swz128(l, cch)) = pk;
; #pragma unroll
;       for (int e = 0; e < 8; ++e) BTi[(cch * 8 + e) * 128 + l] = (bf16_t)(pk[e >> 1] >> (16 * (e & 1)));
;       { const int lc = q >> 4, cc8 = q & 15;
; #pragma unroll
;         for (int kk = 0; kk < 4; ++kk) raw[j][kk] = *(const u32x4*)(P + (t0 + lc - ((tin0 + lc - 3 + kk >= 0) ? (3 - kk) : 0)) * 5120 + 2048 + 2560 + g * 128 + cc8 * 8); }
	global_store_short v[38:39], v35, off offset:512
	global_store_short_d16_hi v[38:39], v35, off offset:768
	global_store_short v[38:39], v36, off offset:1024
	global_store_short_d16_hi v[38:39], v36, off offset:1280
	global_store_short v[38:39], v37, off offset:1536
	global_store_short_d16_hi v[38:39], v37, off offset:1792
	v_lshl_add_u64 v[42:43], s[66:67], 0, v[76:77]
	v_cndmask_b32_e64 v35, -1, 0, s[0:1]
	v_cndmask_b32_e64 v34, -3, 0, s[0:1]
	v_lshl_add_u64 v[34:35], v[34:35], 0, v[42:43]
	v_mov_b64_e32 v[112:113], s[18:19]
	v_mad_u64_u32 v[36:37], s[0:1], v34, s96, v[112:113]
	v_mov_b32_e32 v34, v37
	v_mad_u64_u32 v[34:35], s[0:1], v35, s96, v[34:35]
	v_mov_b32_e32 v37, v34
	s_lshl_b32 s34, s34, 1
	v_lshl_add_u64 v[34:35], v[36:37], 0, s[34:35]
	v_lshl_add_u64 v[34:35], v[34:35], 0, v[0:1]
	s_movk_i32 s4, 0x2000
	v_add_co_u32_e64 v34, s[0:1], s4, v34
	v_cmp_lt_i32_e64 s[58:59], 0, v164
	s_nop 0
	v_addc_co_u32_e64 v35, s[0:1], 0, v35, s[0:1]
	v_cmp_gt_i32_e64 s[0:1], 2, v164
	v_cndmask_b32_e64 v44, 0, 1, s[58:59]
	v_readlane_b32 s5, v253, 17
	v_cndmask_b32_e64 v37, -1, 0, s[0:1]
	v_cndmask_b32_e64 v36, -2, 0, s[0:1]
	v_lshl_add_u64 v[36:37], v[36:37], 0, v[42:43]
	v_mad_u64_u32 v[38:39], s[0:1], v36, s96, v[112:113]
	v_mov_b32_e32 v36, v39
	v_mad_u64_u32 v[36:37], s[0:1], v37, s96, v[36:37]
	v_mov_b32_e32 v39, v36
	v_lshl_add_u64 v[36:37], v[38:39], 0, s[34:35]
	v_lshl_add_u64 v[36:37], v[36:37], 0, v[0:1]
	v_add_co_u32_e64 v36, s[0:1], s4, v36
	v_readlane_b32 s6, v253, 18
	s_nop 0
	v_addc_co_u32_e64 v37, s[0:1], 0, v37, s[0:1]
	v_sub_co_u32_e64 v44, s[0:1], v42, v44
	global_load_dwordx4 v[38:41], v[34:35], off offset:1024
	s_nop 0
	global_load_dwordx4 v[34:37], v[36:37], off offset:1024
	v_subbrev_co_u32_e64 v47, s[0:1], 0, v43, s[0:1]
	v_mad_u64_u32 v[44:45], s[0:1], v44, s96, v[112:113]
	v_mov_b32_e32 v46, v45
	v_mad_u64_u32 v[46:47], s[0:1], v47, s96, v[46:47]
	v_mov_b32_e32 v45, v46
	v_lshl_add_u64 v[44:45], v[44:45], 0, s[34:35]
	v_lshl_add_u64 v[44:45], v[44:45], 0, v[0:1]
	v_add_co_u32_e64 v44, s[0:1], s4, v44
	ds_read_b128 v[166:169], v122
	s_nop 0
	v_addc_co_u32_e64 v45, s[0:1], 0, v45, s[0:1]
	v_mad_u64_u32 v[46:47], s[0:1], v42, s96, v[112:113]
	v_mov_b32_e32 v42, v47
	v_mad_u64_u32 v[42:43], s[0:1], v43, s96, v[42:43]
	v_mov_b32_e32 v47, v42
	v_lshl_add_u64 v[42:43], v[46:47], 0, s[34:35]
	v_lshl_add_u64 v[42:43], v[42:43], 0, v[0:1]
	v_add_co_u32_e64 v42, s[0:1], s4, v42
	s_waitcnt lgkmcnt(0)
	v_pk_mul_f32 v[186:187], v[118:119], v[168:169] op_sel_hi:[0,1]
	v_addc_co_u32_e64 v43, s[0:1], 0, v43, s[0:1]
	global_load_dwordx4 v[46:49], v[44:45], off offset:1024
	s_nop 0
	global_load_dwordx4 v[42:45], v[42:43], off offset:1024
	ds_read_b128 v[170:173], v122 offset:16
	ds_read_b128 v[174:177], v121
	ds_read_b128 v[178:181], v121 offset:16
	ds_read_b128 v[182:185], v122 offset:512
	v_pk_mul_f32 v[188:189], v[118:119], v[166:167] op_sel_hi:[0,1]
	ds_read_b128 v[166:169], v122 offset:528
	s_waitcnt lgkmcnt(4)
	v_pk_mul_f32 v[190:191], v[118:119], v[172:173] op_sel_hi:[0,1]
	v_pk_mul_f32 v[192:193], v[118:119], v[170:171] op_sel_hi:[0,1]
	ds_read_b128 v[170:173], v122 offset:1024
	s_waitcnt lgkmcnt(2)
	v_pk_mul_f32 v[194:195], v[116:117], v[184:185] op_sel_hi:[0,1]
	s_waitcnt lgkmcnt(1)
	v_pk_mul_f32 v[198:199], v[116:117], v[168:169] op_sel_hi:[0,1]
	v_pk_mul_f32 v[222:223], v[116:117], v[166:167] op_sel_hi:[0,1]
	ds_read_b128 v[166:169], v122 offset:1536
	v_pk_mul_f32 v[196:197], v[116:117], v[182:183] op_sel_hi:[0,1]
	ds_read_b128 v[182:185], v122 offset:1040
	s_waitcnt lgkmcnt(2)
	v_pk_mul_f32 v[224:225], v[114:115], v[172:173] op_sel_hi:[0,1]
	s_waitcnt vmcnt(23)
	v_lshlrev_b32_e32 v172, 16, v62
	v_and_b32_e32 v173, 0xffff0000, v62
	v_pk_fma_f32 v[172:173], v[188:189], v[172:173], v[174:175]
	s_waitcnt vmcnt(22)
	v_lshlrev_b32_e32 v174, 16, v58
	v_and_b32_e32 v175, 0xffff0000, v58
	v_pk_mul_f32 v[170:171], v[114:115], v[170:171] op_sel_hi:[0,1]
	v_pk_fma_f32 v[172:173], v[196:197], v[174:175], v[172:173]
	s_waitcnt vmcnt(21)
	v_lshlrev_b32_e32 v174, 16, v54
	v_and_b32_e32 v175, 0xffff0000, v54
	v_pk_fma_f32 v[174:175], v[170:171], v[174:175], v[172:173]
	s_waitcnt vmcnt(20)
	v_lshlrev_b32_e32 v188, 16, v50
	v_and_b32_e32 v189, 0xffff0000, v50
	ds_read_b128 v[170:173], v122 offset:1552
	s_waitcnt lgkmcnt(2)
	v_pk_fma_f32 v[166:167], v[166:167], v[188:189], v[174:175]
	v_lshlrev_b32_e32 v62, 16, v63
	v_mul_f32_e32 v54, 0xbfb8aa3b, v167
	v_exp_f32_e32 v54, v54
	v_and_b32_e32 v63, 0xffff0000, v63
	v_pk_fma_f32 v[62:63], v[186:187], v[62:63], v[176:177]
	v_lshlrev_b32_e32 v58, 16, v59
	v_and_b32_e32 v59, 0xffff0000, v59
	v_add_f32_e32 v165, 1.0, v54
	v_pk_fma_f32 v[58:59], v[194:195], v[58:59], v[62:63]
	v_lshlrev_b32_e32 v54, 16, v55
	v_and_b32_e32 v55, 0xffff0000, v55
	v_pk_fma_f32 v[54:55], v[224:225], v[54:55], v[58:59]
	v_lshlrev_b32_e32 v58, 16, v51
	v_and_b32_e32 v59, 0xffff0000, v51
	v_lshlrev_b32_e32 v62, 16, v64
	v_and_b32_e32 v63, 0xffff0000, v64
	v_pk_fma_f32 v[54:55], v[168:169], v[58:59], v[54:55]
	v_pk_fma_f32 v[62:63], v[192:193], v[62:63], v[178:179]
	v_lshlrev_b32_e32 v168, 16, v60
	v_and_b32_e32 v169, 0xffff0000, v60
	s_waitcnt lgkmcnt(1)
	v_pk_mul_f32 v[174:175], v[114:115], v[182:183] op_sel_hi:[0,1]
	v_pk_fma_f32 v[62:63], v[222:223], v[168:169], v[62:63]
	v_lshlrev_b32_e32 v168, 16, v56
	v_and_b32_e32 v169, 0xffff0000, v56
	v_pk_fma_f32 v[62:63], v[174:175], v[168:169], v[62:63]
	v_lshlrev_b32_e32 v168, 16, v52
	v_and_b32_e32 v169, 0xffff0000, v52
	s_waitcnt lgkmcnt(0)
; DI float silu(float x) { return x * __builtin_amdgcn_rcpf(1.f + __expf(-x)); }
; DI u32x4 pack8(const float (&f)[8]) { u32x4 r; r[0] = pk2(f[0], f[1]); r[1] = pk2(f[2], f[3]); r[2] = pk2(f[4], f[5]); r[3] = pk2(f[6], f[7]); return r; }
; DI void ssd_cb_phase(const bf16_t* P, bf16_t* BT, bf16_t* Cc, bf16_t* CB, const float* dt, float* acs,
;                      const float* cw, const float* cb, const float* A_log, char* lds) {
;     ...
;       const int q = tid + 512 * j, l = q & 127, cch = q >> 7;
;       float v[8];
;       { const f32x4 b0 = *(const f32x4*)(sW + 512 + cch * 8), b1 = *(const f32x4*)(sW + 512 + cch * 8 + 4);
;         v[0] = b0[0]; v[1] = b0[1]; v[2] = b0[2]; v[3] = b0[3]; v[4] = b1[0]; v[5] = b1[1]; v[6] = b1[2]; v[7] = b1[3]; }
; #pragma unroll
;       for (int kk = 0; kk < 4; ++kk) {
;         float f[8]; unpack8(raw[j][kk], f);
;         const float ok = (tin0 + l - 3 + kk >= 0) ? 1.f : 0.f;
;         const f32x4 w0 = *(const f32x4*)(sW + kk * 128 + cch * 8) * ok, w1 = *(const f32x4*)(sW + kk * 128 + cch * 8 + 4) * ok;
;         v[0] += w0[0] * f[0]; v[1] += w0[1] * f[1]; v[2] += w0[2] * f[2]; v[3] += w0[3] * f[3];
;         v[4] += w1[0] * f[4]; v[5] += w1[1] * f[5]; v[6] += w1[2] * f[6]; v[7] += w1[3] * f[7];
;       }
; #pragma unroll
;       for (int e = 0; e < 8; ++e) v[e] = silu(v[e]);
;       const u32x4 pk = pack8(v);
;       *(u32x4*)(sB + swz128(l, cch)) = pk;
; #pragma unroll
;       for (int e = 0; e < 8; ++e) BTi[(cch * 8 + e) * 128 + l] = (bf16_t)(pk[e >> 1] >> (16 * (e & 1)));
;       { const int lc = q >> 4, cc8 = q & 15;
; #pragma unroll
;         for (int kk = 0; kk < 4; ++kk) raw[j][kk] = *(const u32x4*)(P + (t0 + lc - ((tin0 + lc - 3 + kk >= 0) ? (3 - kk) : 0)) * 5120 + 2048 + 2560 + g * 128 + cc8 * 8); }
	v_pk_fma_f32 v[62:63], v[170:171], v[168:169], v[62:63]
	v_mul_f32_e32 v51, 0xbfb8aa3b, v54
	v_mul_f32_e32 v56, 0xbfb8aa3b, v63
	v_exp_f32_e32 v56, v56
	v_lshlrev_b32_e32 v64, 16, v65
	v_and_b32_e32 v65, 0xffff0000, v65
	v_exp_f32_e32 v58, v51
	v_mul_f32_e32 v51, 0xbfb8aa3b, v55
	v_pk_fma_f32 v[64:65], v[190:191], v[64:65], v[180:181]
	v_lshlrev_b32_e32 v60, 16, v61
	v_and_b32_e32 v61, 0xffff0000, v61
	v_pk_mul_f32 v[184:185], v[114:115], v[184:185] op_sel_hi:[0,1]
	v_exp_f32_e32 v59, v51
	v_rcp_f32_e32 v51, v165
	v_add_f32_e32 v165, 1.0, v56
	v_pk_fma_f32 v[60:61], v[198:199], v[60:61], v[64:65]
	v_lshlrev_b32_e32 v56, 16, v57
	v_and_b32_e32 v57, 0xffff0000, v57
	v_pk_fma_f32 v[56:57], v[184:185], v[56:57], v[60:61]
	v_lshlrev_b32_e32 v60, 16, v53
	v_and_b32_e32 v61, 0xffff0000, v53
	v_pk_fma_f32 v[56:57], v[172:173], v[60:61], v[56:57]
	v_mul_f32_e32 v50, 0xbfb8aa3b, v166
	v_mul_f32_e32 v53, 0xbfb8aa3b, v56
	v_mul_f32_e32 v52, 0xbfb8aa3b, v62
	v_exp_f32_e32 v60, v53
	v_mul_f32_e32 v53, 0xbfb8aa3b, v57
	v_exp_f32_e32 v50, v50
	v_exp_f32_e32 v52, v52
	v_exp_f32_e32 v61, v53
	v_add_f32_e32 v58, 1.0, v58
	v_add_f32_e32 v50, 1.0, v50
	v_add_f32_e32 v59, 1.0, v59
	v_add_f32_e32 v52, 1.0, v52
	v_add_f32_e32 v60, 1.0, v60
	v_add_f32_e32 v61, 1.0, v61
	v_rcp_f32_e32 v50, v50
	v_rcp_f32_e32 v58, v58
	v_rcp_f32_e32 v59, v59
	v_rcp_f32_e32 v52, v52
	v_rcp_f32_e32 v53, v165
	v_rcp_f32_e32 v60, v60
	v_rcp_f32_e32 v61, v61
	v_pk_mul_f32 v[50:51], v[166:167], v[50:51]
	v_pk_mul_f32 v[54:55], v[54:55], v[58:59]
	v_pk_mul_f32 v[52:53], v[62:63], v[52:53]
	v_pk_mul_f32 v[56:57], v[56:57], v[60:61]
	v_add_u32_e32 v165, s78, v78
	v_cvt_pk_bf16_f32 v50, v50, v51
	v_cvt_pk_bf16_f32 v51, v54, v55
	v_cvt_pk_bf16_f32 v52, v52, v53
	v_cvt_pk_bf16_f32 v53, v56, v57
	v_lshl_add_u64 v[54:55], v[86:87], 1, s[64:65]
	v_cmp_gt_i32_e64 s[0:1], 3, v165
	ds_write_b128 v157, v[50:53]
	global_store_short v[54:55], v50, off
	global_store_short_d16_hi v[54:55], v50, off offset:256
	global_store_short v[54:55], v51, off offset:512
	global_store_short_d16_hi v[54:55], v51, off offset:768
	global_store_short v[54:55], v52, off offset:1024
	global_store_short_d16_hi v[54:55], v52, off offset:1280
	global_store_short v[54:55], v53, off offset:1536
	global_store_short_d16_hi v[54:55], v53, off offset:1792
	v_lshl_add_u64 v[58:59], s[66:67], 0, v[78:79]
	v_cndmask_b32_e64 v51, -1, 0, s[0:1]
	v_cndmask_b32_e64 v50, -3, 0, s[0:1]
	v_lshl_add_u64 v[50:51], v[50:51], 0, v[58:59]
	v_mad_u64_u32 v[52:53], s[0:1], v50, s96, v[112:113]
	v_mov_b32_e32 v50, v53
	v_mad_u64_u32 v[50:51], s[0:1], v51, s96, v[50:51]
	v_mov_b32_e32 v53, v50
	v_lshl_add_u64 v[50:51], v[52:53], 0, s[34:35]
	v_lshl_add_u64 v[50:51], v[50:51], 0, v[0:1]
	v_add_co_u32_e64 v50, s[0:1], s4, v50
	v_cmp_lt_i32_e64 s[60:61], 0, v165
	s_nop 0
	v_addc_co_u32_e64 v51, s[0:1], 0, v51, s[0:1]
	v_cmp_gt_i32_e64 s[0:1], 2, v165
	v_cndmask_b32_e64 v60, 0, 1, s[60:61]
	s_waitcnt vmcnt(11)
	v_lshlrev_b32_e32 v230, 16, v38
	v_cndmask_b32_e64 v53, -1, 0, s[0:1]
	v_cndmask_b32_e64 v52, -2, 0, s[0:1]
	v_lshl_add_u64 v[52:53], v[52:53], 0, v[58:59]
	v_mad_u64_u32 v[54:55], s[0:1], v52, s96, v[112:113]
	v_mov_b32_e32 v52, v55
	v_mad_u64_u32 v[52:53], s[0:1], v53, s96, v[52:53]
	v_mov_b32_e32 v55, v52
	v_lshl_add_u64 v[52:53], v[54:55], 0, s[34:35]
	v_lshl_add_u64 v[52:53], v[52:53], 0, v[0:1]
	v_add_co_u32_e64 v52, s[0:1], s4, v52
	v_and_b32_e32 v231, 0xffff0000, v38
	s_nop 0
	v_addc_co_u32_e64 v53, s[0:1], 0, v53, s[0:1]
	v_sub_co_u32_e64 v60, s[0:1], v58, v60
	global_load_dwordx4 v[54:57], v[50:51], off offset:1024
	s_nop 0
	global_load_dwordx4 v[50:53], v[52:53], off offset:1024
	v_subbrev_co_u32_e64 v63, s[0:1], 0, v59, s[0:1]
	v_mad_u64_u32 v[60:61], s[0:1], v60, s96, v[112:113]
	v_mov_b32_e32 v62, v61
	v_mad_u64_u32 v[62:63], s[0:1], v63, s96, v[62:63]
	v_mov_b32_e32 v61, v62
	v_lshl_add_u64 v[60:61], v[60:61], 0, s[34:35]
	v_lshl_add_u64 v[60:61], v[60:61], 0, v[0:1]
	v_add_co_u32_e64 v60, s[0:1], s4, v60
	ds_read_b128 v[166:169], v124
	s_nop 0
	v_addc_co_u32_e64 v61, s[0:1], 0, v61, s[0:1]
	v_mad_u64_u32 v[62:63], s[0:1], v58, s96, v[112:113]
	v_mov_b32_e32 v58, v63
	v_mad_u64_u32 v[58:59], s[0:1], v59, s96, v[58:59]
	v_mov_b32_e32 v63, v58
	v_lshl_add_u64 v[58:59], v[62:63], 0, s[34:35]
	v_lshl_add_u64 v[58:59], v[58:59], 0, v[0:1]
	v_add_co_u32_e64 v58, s[0:1], s4, v58
	s_waitcnt lgkmcnt(0)
	v_pk_mul_f32 v[186:187], v[118:119], v[168:169] op_sel_hi:[0,1]
	v_addc_co_u32_e64 v59, s[0:1], 0, v59, s[0:1]
	global_load_dwordx4 v[62:65], v[60:61], off offset:1024
	s_nop 0
	global_load_dwordx4 v[58:61], v[58:59], off offset:1024
	ds_read_b128 v[170:173], v124 offset:16
	ds_read_b128 v[174:177], v123
	ds_read_b128 v[178:181], v123 offset:16
	ds_read_b128 v[182:185], v124 offset:512
	v_pk_mul_f32 v[188:189], v[118:119], v[166:167] op_sel_hi:[0,1]
	ds_read_b128 v[166:169], v124 offset:528
	s_waitcnt lgkmcnt(4)
	v_pk_mul_f32 v[190:191], v[118:119], v[172:173] op_sel_hi:[0,1]
	v_pk_mul_f32 v[192:193], v[118:119], v[170:171] op_sel_hi:[0,1]
	ds_read_b128 v[170:173], v124 offset:1024
	s_waitcnt lgkmcnt(2)
	v_pk_mul_f32 v[194:195], v[116:117], v[184:185] op_sel_hi:[0,1]
	s_waitcnt lgkmcnt(1)
	v_pk_mul_f32 v[198:199], v[116:117], v[168:169] op_sel_hi:[0,1]
	v_pk_mul_f32 v[222:223], v[116:117], v[166:167] op_sel_hi:[0,1]
	ds_read_b128 v[166:169], v124 offset:1536
	v_pk_mul_f32 v[196:197], v[116:117], v[182:183] op_sel_hi:[0,1]
	ds_read_b128 v[182:185], v124 offset:1040
	s_waitcnt lgkmcnt(2)
; DI float silu(float x) { return x * __builtin_amdgcn_rcpf(1.f + __expf(-x)); }
; DI u32x4 pack8(const float (&f)[8]) { u32x4 r; r[0] = pk2(f[0], f[1]); r[1] = pk2(f[2], f[3]); r[2] = pk2(f[4], f[5]); r[3] = pk2(f[6], f[7]); return r; }
; DI void ssd_cb_phase(const bf16_t* P, bf16_t* BT, bf16_t* Cc, bf16_t* CB, const float* dt, float* acs,
;                      const float* cw, const float* cb, const float* A_log, char* lds) {
;     ...
;       const int q = tid + 512 * j, l = q & 127, cch = q >> 7;
;       float v[8];
;       { const f32x4 b0 = *(const f32x4*)(sW + 512 + cch * 8), b1 = *(const f32x4*)(sW + 512 + cch * 8 + 4);
;         v[0] = b0[0]; v[1] = b0[1]; v[2] = b0[2]; v[3] = b0[3]; v[4] = b1[0]; v[5] = b1[1]; v[6] = b1[2]; v[7] = b1[3]; }
; #pragma unroll
;       for (int kk = 0; kk < 4; ++kk) {
;         float f[8]; unpack8(raw[j][kk], f);
;         const float ok = (tin0 + l - 3 + kk >= 0) ? 1.f : 0.f;
;         const f32x4 w0 = *(const f32x4*)(sW + kk * 128 + cch * 8) * ok, w1 = *(const f32x4*)(sW + kk * 128 + cch * 8 + 4) * ok;
;         v[0] += w0[0] * f[0]; v[1] += w0[1] * f[1]; v[2] += w0[2] * f[2]; v[3] += w0[3] * f[3];
;         v[4] += w1[0] * f[4]; v[5] += w1[1] * f[5]; v[6] += w1[2] * f[6]; v[7] += w1[3] * f[7];
;       }
; #pragma unroll
;       for (int e = 0; e < 8; ++e) v[e] = silu(v[e]);
;       const u32x4 pk = pack8(v);
;       *(u32x4*)(sB + swz128(l, cch)) = pk;
; #pragma unroll
;       for (int e = 0; e < 8; ++e) BTi[(cch * 8 + e) * 128 + l] = (bf16_t)(pk[e >> 1] >> (16 * (e & 1)));
;       { const int lc = q >> 4, cc8 = q & 15;
; #pragma unroll
;         for (int kk = 0; kk < 4; ++kk) raw[j][kk] = *(const u32x4*)(P + (t0 + lc - ((tin0 + lc - 3 + kk >= 0) ? (3 - kk) : 0)) * 5120 + 2048 + 2560 + g * 128 + cc8 * 8); }
	v_pk_mul_f32 v[224:225], v[114:115], v[172:173] op_sel_hi:[0,1]
	v_lshlrev_b32_e32 v172, 16, v30
	v_and_b32_e32 v173, 0xffff0000, v30
	v_pk_fma_f32 v[172:173], v[188:189], v[172:173], v[174:175]
	v_lshlrev_b32_e32 v174, 16, v26
	v_and_b32_e32 v175, 0xffff0000, v26
	v_pk_mul_f32 v[170:171], v[114:115], v[170:171] op_sel_hi:[0,1]
	v_pk_fma_f32 v[172:173], v[196:197], v[174:175], v[172:173]
	v_lshlrev_b32_e32 v174, 16, v22
	v_and_b32_e32 v175, 0xffff0000, v22
	v_pk_fma_f32 v[174:175], v[170:171], v[174:175], v[172:173]
	v_lshlrev_b32_e32 v188, 16, v18
	v_and_b32_e32 v189, 0xffff0000, v18
	ds_read_b128 v[170:173], v124 offset:1552
	s_waitcnt lgkmcnt(2)
	v_pk_fma_f32 v[166:167], v[166:167], v[188:189], v[174:175]
	v_lshlrev_b32_e32 v30, 16, v31
	v_mul_f32_e32 v22, 0xbfb8aa3b, v167
	v_exp_f32_e32 v22, v22
	v_and_b32_e32 v31, 0xffff0000, v31
	v_pk_fma_f32 v[30:31], v[186:187], v[30:31], v[176:177]
	v_lshlrev_b32_e32 v26, 16, v27
	v_and_b32_e32 v27, 0xffff0000, v27
	s_waitcnt lgkmcnt(1)
	v_pk_mul_f32 v[174:175], v[114:115], v[182:183] op_sel_hi:[0,1]
	v_add_f32_e32 v182, 1.0, v22
	v_pk_fma_f32 v[26:27], v[194:195], v[26:27], v[30:31]
	v_lshlrev_b32_e32 v22, 16, v23
	v_and_b32_e32 v23, 0xffff0000, v23
	v_pk_fma_f32 v[22:23], v[224:225], v[22:23], v[26:27]
	v_lshlrev_b32_e32 v26, 16, v19
	v_and_b32_e32 v27, 0xffff0000, v19
	v_lshlrev_b32_e32 v30, 16, v32
	v_and_b32_e32 v31, 0xffff0000, v32
	v_pk_fma_f32 v[22:23], v[168:169], v[26:27], v[22:23]
	v_pk_fma_f32 v[30:31], v[192:193], v[30:31], v[178:179]
	v_lshlrev_b32_e32 v168, 16, v28
	v_and_b32_e32 v169, 0xffff0000, v28
	v_pk_fma_f32 v[30:31], v[222:223], v[168:169], v[30:31]
	v_lshlrev_b32_e32 v168, 16, v24
	v_and_b32_e32 v169, 0xffff0000, v24
	v_pk_fma_f32 v[30:31], v[174:175], v[168:169], v[30:31]
	v_lshlrev_b32_e32 v168, 16, v20
	v_and_b32_e32 v169, 0xffff0000, v20
	s_waitcnt lgkmcnt(0)
	v_pk_fma_f32 v[30:31], v[170:171], v[168:169], v[30:31]
	v_lshlrev_b32_e32 v32, 16, v33
	v_mul_f32_e32 v24, 0xbfb8aa3b, v31
	v_exp_f32_e32 v24, v24
	v_and_b32_e32 v33, 0xffff0000, v33
	v_pk_fma_f32 v[32:33], v[190:191], v[32:33], v[180:181]
	v_lshlrev_b32_e32 v28, 16, v29
	v_and_b32_e32 v29, 0xffff0000, v29
	v_pk_mul_f32 v[184:185], v[114:115], v[184:185] op_sel_hi:[0,1]
	v_add_f32_e32 v168, 1.0, v24
	v_pk_fma_f32 v[28:29], v[198:199], v[28:29], v[32:33]
	v_lshlrev_b32_e32 v24, 16, v25
	v_and_b32_e32 v25, 0xffff0000, v25
	v_pk_fma_f32 v[24:25], v[184:185], v[24:25], v[28:29]
	v_lshlrev_b32_e32 v28, 16, v21
	v_and_b32_e32 v29, 0xffff0000, v21
	v_pk_fma_f32 v[24:25], v[172:173], v[28:29], v[24:25]
	v_mul_f32_e32 v19, 0xbfb8aa3b, v22
	v_mul_f32_e32 v21, 0xbfb8aa3b, v24
	v_mul_f32_e32 v18, 0xbfb8aa3b, v166
	v_exp_f32_e32 v26, v19
	v_mul_f32_e32 v19, 0xbfb8aa3b, v23
	v_mul_f32_e32 v20, 0xbfb8aa3b, v30
	v_exp_f32_e32 v28, v21
	v_mul_f32_e32 v21, 0xbfb8aa3b, v25
	v_exp_f32_e32 v18, v18
	v_exp_f32_e32 v27, v19
	v_exp_f32_e32 v20, v20
	v_exp_f32_e32 v29, v21
	v_add_f32_e32 v18, 1.0, v18
	v_add_f32_e32 v26, 1.0, v26
	v_add_f32_e32 v27, 1.0, v27
	v_add_f32_e32 v20, 1.0, v20
	v_add_f32_e32 v28, 1.0, v28
	v_add_f32_e32 v29, 1.0, v29
	v_rcp_f32_e32 v18, v18
	v_rcp_f32_e32 v19, v182
	v_rcp_f32_e32 v26, v26
	v_rcp_f32_e32 v27, v27
	v_rcp_f32_e32 v20, v20
	v_rcp_f32_e32 v21, v168
	v_rcp_f32_e32 v28, v28
	v_rcp_f32_e32 v29, v29
	v_pk_mul_f32 v[18:19], v[166:167], v[18:19]
	v_pk_mul_f32 v[22:23], v[22:23], v[26:27]
	v_pk_mul_f32 v[20:21], v[30:31], v[20:21]
	v_pk_mul_f32 v[24:25], v[24:25], v[28:29]
	v_add_u32_e32 v166, s78, v80
	v_cvt_pk_bf16_f32 v18, v18, v19
	v_cvt_pk_bf16_f32 v19, v22, v23
	v_cvt_pk_bf16_f32 v20, v20, v21
	v_cvt_pk_bf16_f32 v21, v24, v25
	v_lshl_add_u64 v[22:23], v[88:89], 1, s[64:65]
	v_cmp_gt_i32_e64 s[0:1], 3, v166
	ds_write_b128 v158, v[18:21]
	global_store_short v[22:23], v18, off
	global_store_short_d16_hi v[22:23], v18, off offset:256
	global_store_short v[22:23], v19, off offset:512
	global_store_short_d16_hi v[22:23], v19, off offset:768
	global_store_short v[22:23], v20, off offset:1024
	global_store_short_d16_hi v[22:23], v20, off offset:1280
	global_store_short v[22:23], v21, off offset:1536
	global_store_short_d16_hi v[22:23], v21, off offset:1792
	v_lshl_add_u64 v[26:27], s[66:67], 0, v[80:81]
	v_cndmask_b32_e64 v19, -1, 0, s[0:1]
	v_cndmask_b32_e64 v18, -3, 0, s[0:1]
	v_lshl_add_u64 v[18:19], v[18:19], 0, v[26:27]
	v_mad_u64_u32 v[20:21], s[0:1], v18, s96, v[112:113]
	v_mov_b32_e32 v18, v21
	v_mad_u64_u32 v[18:19], s[0:1], v19, s96, v[18:19]
	v_mov_b32_e32 v21, v18
	v_lshl_add_u64 v[18:19], v[20:21], 0, s[34:35]
	v_lshl_add_u64 v[18:19], v[18:19], 0, v[0:1]
	v_add_co_u32_e64 v18, s[0:1], s4, v18
	v_cmp_lt_i32_e64 s[62:63], 0, v166
	s_nop 0
	v_addc_co_u32_e64 v19, s[0:1], 0, v19, s[0:1]
	v_cmp_gt_i32_e64 s[0:1], 2, v166
	v_cndmask_b32_e64 v28, 0, 1, s[62:63]
	v_readlane_b32 s7, v253, 19
	v_cndmask_b32_e64 v21, -1, 0, s[0:1]
	v_cndmask_b32_e64 v20, -2, 0, s[0:1]
	v_lshl_add_u64 v[20:21], v[20:21], 0, v[26:27]
	v_mad_u64_u32 v[22:23], s[0:1], v20, s96, v[112:113]
	v_mov_b32_e32 v20, v23
	v_mad_u64_u32 v[20:21], s[0:1], v21, s96, v[20:21]
	v_mov_b32_e32 v23, v20
	v_lshl_add_u64 v[20:21], v[22:23], 0, s[34:35]
	v_lshl_add_u64 v[20:21], v[20:21], 0, v[0:1]
	v_add_co_u32_e64 v20, s[0:1], s4, v20
	v_readlane_b32 s8, v253, 20
	s_nop 0
	v_addc_co_u32_e64 v21, s[0:1], 0, v21, s[0:1]
	v_sub_co_u32_e64 v28, s[0:1], v26, v28
	global_load_dwordx4 v[22:25], v[18:19], off offset:1024
	s_nop 0
	global_load_dwordx4 v[18:21], v[20:21], off offset:1024
	v_subbrev_co_u32_e64 v31, s[0:1], 0, v27, s[0:1]
	v_mad_u64_u32 v[28:29], s[0:1], v28, s96, v[112:113]
	v_mov_b32_e32 v30, v29
	v_mad_u64_u32 v[30:31], s[0:1], v31, s96, v[30:31]
	v_mov_b32_e32 v29, v30
	v_lshl_add_u64 v[28:29], v[28:29], 0, s[34:35]
	v_lshl_add_u64 v[28:29], v[28:29], 0, v[0:1]
	v_add_co_u32_e64 v28, s[0:1], s4, v28
	ds_read_b128 v[168:171], v126
	s_nop 0
	v_addc_co_u32_e64 v29, s[0:1], 0, v29, s[0:1]
	v_mad_u64_u32 v[30:31], s[0:1], v26, s96, v[112:113]
	v_mov_b32_e32 v26, v31
	v_mad_u64_u32 v[26:27], s[0:1], v27, s96, v[26:27]
	v_mov_b32_e32 v31, v26
	v_lshl_add_u64 v[26:27], v[30:31], 0, s[34:35]
	v_lshl_add_u64 v[26:27], v[26:27], 0, v[0:1]
	v_add_co_u32_e64 v26, s[0:1], s4, v26
	s_waitcnt lgkmcnt(0)
; DI float silu(float x) { return x * __builtin_amdgcn_rcpf(1.f + __expf(-x)); }
; DI u32x4 pack8(const float (&f)[8]) { u32x4 r; r[0] = pk2(f[0], f[1]); r[1] = pk2(f[2], f[3]); r[2] = pk2(f[4], f[5]); r[3] = pk2(f[6], f[7]); return r; }
; DI void ssd_cb_phase(const bf16_t* P, bf16_t* BT, bf16_t* Cc, bf16_t* CB, const float* dt, float* acs,
;                      const float* cw, const float* cb, const float* A_log, char* lds) {
;     ...
;       const int q = tid + 512 * j, l = q & 127, cch = q >> 7;
;       float v[8];
;       { const f32x4 b0 = *(const f32x4*)(sW + 512 + cch * 8), b1 = *(const f32x4*)(sW + 512 + cch * 8 + 4);
;         v[0] = b0[0]; v[1] = b0[1]; v[2] = b0[2]; v[3] = b0[3]; v[4] = b1[0]; v[5] = b1[1]; v[6] = b1[2]; v[7] = b1[3]; }
; #pragma unroll
;       for (int kk = 0; kk < 4; ++kk) {
;         float f[8]; unpack8(raw[j][kk], f);
;         const float ok = (tin0 + l - 3 + kk >= 0) ? 1.f : 0.f;
;         const f32x4 w0 = *(const f32x4*)(sW + kk * 128 + cch * 8) * ok, w1 = *(const f32x4*)(sW + kk * 128 + cch * 8 + 4) * ok;
;         v[0] += w0[0] * f[0]; v[1] += w0[1] * f[1]; v[2] += w0[2] * f[2]; v[3] += w0[3] * f[3];
;         v[4] += w1[0] * f[4]; v[5] += w1[1] * f[5]; v[6] += w1[2] * f[6]; v[7] += w1[3] * f[7];
;       }
; #pragma unroll
;       for (int e = 0; e < 8; ++e) v[e] = silu(v[e]);
;       const u32x4 pk = pack8(v);
;       *(u32x4*)(sB + swz128(l, cch)) = pk;
; #pragma unroll
;       for (int e = 0; e < 8; ++e) BTi[(cch * 8 + e) * 128 + l] = (bf16_t)(pk[e >> 1] >> (16 * (e & 1)));
;       { const int lc = q >> 4, cc8 = q & 15;
; #pragma unroll
;         for (int kk = 0; kk < 4; ++kk) raw[j][kk] = *(const u32x4*)(P + (t0 + lc - ((tin0 + lc - 3 + kk >= 0) ? (3 - kk) : 0)) * 5120 + 2048 + 2560 + g * 128 + cc8 * 8); }
	v_pk_mul_f32 v[188:189], v[118:119], v[170:171] op_sel_hi:[0,1]
	v_addc_co_u32_e64 v27, s[0:1], 0, v27, s[0:1]
	global_load_dwordx4 v[30:33], v[28:29], off offset:1024
	s_nop 0
	global_load_dwordx4 v[26:29], v[26:27], off offset:1024
	ds_read_b128 v[172:175], v126 offset:16
	ds_read_b128 v[176:179], v125
	ds_read_b128 v[180:183], v125 offset:16
	ds_read_b128 v[184:187], v126 offset:512
	v_pk_mul_f32 v[190:191], v[118:119], v[168:169] op_sel_hi:[0,1]
	ds_read_b128 v[168:171], v126 offset:528
	s_waitcnt lgkmcnt(4)
	v_pk_mul_f32 v[192:193], v[118:119], v[174:175] op_sel_hi:[0,1]
	v_pk_mul_f32 v[194:195], v[118:119], v[172:173] op_sel_hi:[0,1]
	ds_read_b128 v[172:175], v126 offset:1024
	s_waitcnt lgkmcnt(2)
	v_pk_mul_f32 v[196:197], v[116:117], v[186:187] op_sel_hi:[0,1]
	s_waitcnt lgkmcnt(1)
	v_pk_mul_f32 v[222:223], v[116:117], v[170:171] op_sel_hi:[0,1]
	v_pk_mul_f32 v[224:225], v[116:117], v[168:169] op_sel_hi:[0,1]
	ds_read_b128 v[168:171], v126 offset:1536
	v_pk_mul_f32 v[198:199], v[116:117], v[184:185] op_sel_hi:[0,1]
	ds_read_b128 v[184:187], v126 offset:1040
	s_waitcnt lgkmcnt(2)
	v_pk_mul_f32 v[226:227], v[114:115], v[174:175] op_sel_hi:[0,1]
	v_lshlrev_b32_e32 v174, 16, v14
	v_and_b32_e32 v175, 0xffff0000, v14
	v_pk_fma_f32 v[174:175], v[190:191], v[174:175], v[176:177]
	v_lshlrev_b32_e32 v176, 16, v10
	v_and_b32_e32 v177, 0xffff0000, v10
	v_pk_mul_f32 v[172:173], v[114:115], v[172:173] op_sel_hi:[0,1]
	v_pk_fma_f32 v[174:175], v[198:199], v[176:177], v[174:175]
	v_lshlrev_b32_e32 v176, 16, v6
	v_and_b32_e32 v177, 0xffff0000, v6
	v_pk_fma_f32 v[176:177], v[172:173], v[176:177], v[174:175]
	v_lshlrev_b32_e32 v190, 16, v2
	v_and_b32_e32 v191, 0xffff0000, v2
	ds_read_b128 v[172:175], v126 offset:1552
	s_waitcnt lgkmcnt(2)
	v_pk_fma_f32 v[168:169], v[168:169], v[190:191], v[176:177]
	v_lshlrev_b32_e32 v14, 16, v15
	v_mul_f32_e32 v6, 0xbfb8aa3b, v169
	v_exp_f32_e32 v6, v6
	v_and_b32_e32 v15, 0xffff0000, v15
	v_pk_fma_f32 v[14:15], v[188:189], v[14:15], v[178:179]
	v_lshlrev_b32_e32 v10, 16, v11
	v_and_b32_e32 v11, 0xffff0000, v11
	s_waitcnt lgkmcnt(1)
	v_pk_mul_f32 v[186:187], v[114:115], v[186:187] op_sel_hi:[0,1]
	v_pk_mul_f32 v[176:177], v[114:115], v[184:185] op_sel_hi:[0,1]
	v_add_f32_e32 v114, 1.0, v6
	v_pk_fma_f32 v[10:11], v[196:197], v[10:11], v[14:15]
	v_lshlrev_b32_e32 v6, 16, v7
	v_and_b32_e32 v7, 0xffff0000, v7
	v_pk_fma_f32 v[6:7], v[226:227], v[6:7], v[10:11]
	v_lshlrev_b32_e32 v10, 16, v3
	v_and_b32_e32 v11, 0xffff0000, v3
	v_lshlrev_b32_e32 v14, 16, v16
	v_and_b32_e32 v15, 0xffff0000, v16
	v_pk_fma_f32 v[6:7], v[170:171], v[10:11], v[6:7]
	v_pk_fma_f32 v[14:15], v[194:195], v[14:15], v[180:181]
	v_lshlrev_b32_e32 v170, 16, v12
	v_and_b32_e32 v171, 0xffff0000, v12
	v_pk_fma_f32 v[14:15], v[224:225], v[170:171], v[14:15]
	v_lshlrev_b32_e32 v170, 16, v8
	v_and_b32_e32 v171, 0xffff0000, v8
	v_pk_fma_f32 v[14:15], v[176:177], v[170:171], v[14:15]
	v_lshlrev_b32_e32 v170, 16, v4
	v_and_b32_e32 v171, 0xffff0000, v4
	s_waitcnt lgkmcnt(0)
	v_pk_fma_f32 v[14:15], v[172:173], v[170:171], v[14:15]
	v_mul_f32_e32 v3, 0xbfb8aa3b, v6
	v_mul_f32_e32 v8, 0xbfb8aa3b, v15
	v_exp_f32_e32 v8, v8
	v_lshlrev_b32_e32 v16, 16, v17
	v_and_b32_e32 v17, 0xffff0000, v17
	v_exp_f32_e32 v10, v3
	v_mul_f32_e32 v3, 0xbfb8aa3b, v7
	v_pk_fma_f32 v[16:17], v[192:193], v[16:17], v[182:183]
	v_lshlrev_b32_e32 v12, 16, v13
	v_and_b32_e32 v13, 0xffff0000, v13
	v_exp_f32_e32 v11, v3
	v_rcp_f32_e32 v3, v114
	v_add_f32_e32 v114, 1.0, v8
	v_pk_fma_f32 v[12:13], v[222:223], v[12:13], v[16:17]
	v_lshlrev_b32_e32 v8, 16, v9
	v_and_b32_e32 v9, 0xffff0000, v9
	v_pk_fma_f32 v[8:9], v[186:187], v[8:9], v[12:13]
	v_lshlrev_b32_e32 v12, 16, v5
	v_and_b32_e32 v13, 0xffff0000, v5
	v_pk_fma_f32 v[8:9], v[174:175], v[12:13], v[8:9]
	v_mul_f32_e32 v2, 0xbfb8aa3b, v168
	v_mul_f32_e32 v5, 0xbfb8aa3b, v8
	v_mul_f32_e32 v4, 0xbfb8aa3b, v14
	v_exp_f32_e32 v12, v5
	v_mul_f32_e32 v5, 0xbfb8aa3b, v9
	v_exp_f32_e32 v2, v2
	v_exp_f32_e32 v4, v4
	v_exp_f32_e32 v13, v5
	v_add_f32_e32 v10, 1.0, v10
	v_add_f32_e32 v2, 1.0, v2
	v_add_f32_e32 v11, 1.0, v11
	v_add_f32_e32 v4, 1.0, v4
	v_add_f32_e32 v12, 1.0, v12
	v_add_f32_e32 v13, 1.0, v13
	v_rcp_f32_e32 v2, v2
	v_rcp_f32_e32 v10, v10
	v_rcp_f32_e32 v11, v11
	v_rcp_f32_e32 v4, v4
	v_rcp_f32_e32 v5, v114
	v_rcp_f32_e32 v12, v12
	v_rcp_f32_e32 v13, v13
	v_pk_mul_f32 v[2:3], v[168:169], v[2:3]
	v_pk_mul_f32 v[6:7], v[6:7], v[10:11]
	v_pk_mul_f32 v[4:5], v[14:15], v[4:5]
	v_pk_mul_f32 v[8:9], v[8:9], v[12:13]
	v_add_u32_e32 v114, s78, v82
	v_cvt_pk_bf16_f32 v2, v2, v3
	v_cvt_pk_bf16_f32 v3, v6, v7
	v_cvt_pk_bf16_f32 v4, v4, v5
	v_cvt_pk_bf16_f32 v5, v8, v9
	v_lshl_add_u64 v[6:7], v[90:91], 1, s[64:65]
	v_cmp_gt_i32_e64 s[0:1], 3, v114
	ds_write_b128 v159, v[2:5]
	global_store_short v[6:7], v2, off
	global_store_short_d16_hi v[6:7], v2, off offset:256
	global_store_short v[6:7], v3, off offset:512
	global_store_short_d16_hi v[6:7], v3, off offset:768
	global_store_short v[6:7], v4, off offset:1024
	global_store_short_d16_hi v[6:7], v4, off offset:1280
	global_store_short v[6:7], v5, off offset:1536
	global_store_short_d16_hi v[6:7], v5, off offset:1792
	v_lshl_add_u64 v[10:11], s[66:67], 0, v[82:83]
	v_cndmask_b32_e64 v3, -1, 0, s[0:1]
	v_cndmask_b32_e64 v2, -3, 0, s[0:1]
	v_lshl_add_u64 v[2:3], v[2:3], 0, v[10:11]
	v_mad_u64_u32 v[4:5], s[0:1], v2, s96, v[112:113]
	v_mov_b32_e32 v2, v5
	v_mad_u64_u32 v[2:3], s[0:1], v3, s96, v[2:3]
	v_mov_b32_e32 v5, v2
	v_lshl_add_u64 v[2:3], v[4:5], 0, s[34:35]
	v_lshl_add_u64 v[2:3], v[2:3], 0, v[0:1]
	v_add_co_u32_e64 v2, s[0:1], s4, v2
	v_cmp_lt_i32_e64 s[64:65], 0, v114
	s_nop 0
	v_addc_co_u32_e64 v3, s[0:1], 0, v3, s[0:1]
	v_cmp_gt_i32_e64 s[0:1], 2, v114
	v_cndmask_b32_e64 v12, 0, 1, s[64:65]
	s_waitcnt vmcnt(11)
; DI void ssd_cb_phase(const bf16_t* P, bf16_t* BT, bf16_t* Cc, bf16_t* CB, const float* dt, float* acs,
;                      const float* cw, const float* cb, const float* A_log, char* lds) {
;     ...
;       { const int lc = q >> 4, cc8 = q & 15;
; #pragma unroll
;         for (int kk = 0; kk < 4; ++kk) raw[j][kk] = *(const u32x4*)(P + (t0 + lc - ((tin0 + lc - 3 + kk >= 0) ? (3 - kk) : 0)) * 5120 + 2048 + 2560 + g * 128 + cc8 * 8); }
;     }
; #pragma unroll
;     for (int j = 0; j < 4; ++j) {
;       const int q = tid + 512 * j, l = q >> 4, cch = q & 15;
;       float v[8];
;       { const f32x4 b0 = *(const f32x4*)(sW + 640 + 512 + cch * 8), b1 = *(const f32x4*)(sW + 640 + 512 + cch * 8 + 4);
;         v[0] = b0[0]; v[1] = b0[1]; v[2] = b0[2]; v[3] = b0[3]; v[4] = b1[0]; v[5] = b1[1]; v[6] = b1[2]; v[7] = b1[3]; }
; #pragma unroll
;       for (int kk = 0; kk < 4; ++kk) {
;         float f[8]; unpack8(raw[j][kk], f);
;         const float ok = (tin0 + l - 3 + kk >= 0) ? 1.f : 0.f;
;         const f32x4 w0 = *(const f32x4*)(sW + 640 + kk * 128 + cch * 8) * ok, w1 = *(const f32x4*)(sW + 640 + kk * 128 + cch * 8 + 4) * ok;
;         v[0] += w0[0] * f[0]; v[1] += w0[1] * f[1]; v[2] += w0[2] * f[2]; v[3] += w0[3] * f[3];
;         v[4] += w1[0] * f[4]; v[5] += w1[1] * f[5]; v[6] += w1[2] * f[6]; v[7] += w1[3] * f[7];
	v_and_b32_e32 v167, 0xffff0000, v22
	v_cndmask_b32_e64 v5, -1, 0, s[0:1]
	v_cndmask_b32_e64 v4, -2, 0, s[0:1]
	v_lshl_add_u64 v[4:5], v[4:5], 0, v[10:11]
	v_mad_u64_u32 v[6:7], s[0:1], v4, s96, v[112:113]
	v_mov_b32_e32 v4, v7
	v_mad_u64_u32 v[4:5], s[0:1], v5, s96, v[4:5]
	v_mov_b32_e32 v7, v4
	v_lshl_add_u64 v[4:5], v[6:7], 0, s[34:35]
	v_lshl_add_u64 v[4:5], v[4:5], 0, v[0:1]
	v_add_co_u32_e64 v4, s[0:1], s4, v4
	v_readlane_b32 s9, v253, 21
	s_nop 0
	v_addc_co_u32_e64 v5, s[0:1], 0, v5, s[0:1]
	v_sub_co_u32_e64 v12, s[0:1], v10, v12
	global_load_dwordx4 v[6:9], v[2:3], off offset:1024
	s_nop 0
	global_load_dwordx4 v[2:5], v[4:5], off offset:1024
	v_subbrev_co_u32_e64 v15, s[0:1], 0, v11, s[0:1]
	v_mad_u64_u32 v[12:13], s[0:1], v12, s96, v[112:113]
	v_mov_b32_e32 v14, v13
	v_mad_u64_u32 v[14:15], s[0:1], v15, s96, v[14:15]
	v_mov_b32_e32 v13, v14
	v_lshl_add_u64 v[12:13], v[12:13], 0, s[34:35]
	v_lshl_add_u64 v[12:13], v[12:13], 0, v[0:1]
	v_add_co_u32_e64 v12, s[0:1], s4, v12
	v_readlane_b32 s10, v253, 22
	s_nop 0
	v_addc_co_u32_e64 v13, s[0:1], 0, v13, s[0:1]
	v_mad_u64_u32 v[14:15], s[0:1], v10, s96, v[112:113]
	v_mov_b32_e32 v10, v15
	v_mad_u64_u32 v[10:11], s[0:1], v11, s96, v[10:11]
	v_mov_b32_e32 v15, v10
	v_lshl_add_u64 v[10:11], v[14:15], 0, s[34:35]
	v_lshl_add_u64 v[10:11], v[10:11], 0, v[0:1]
	v_add_co_u32_e64 v10, s[0:1], s4, v10
	v_lshl_add_u64 v[112:113], v[70:71], 0, s[68:69]
	s_nop 0
	v_addc_co_u32_e64 v11, s[0:1], 0, v11, s[0:1]
	global_load_dwordx4 v[14:17], v[12:13], off offset:1024
	s_nop 0
	global_load_dwordx4 v[10:13], v[10:11], off offset:1024
	ds_read_b128 v[168:171], v115
	ds_read_b128 v[172:175], v73
	ds_read_b128 v[176:179], v73 offset:16
	ds_read_b128 v[180:183], v115 offset:16
	v_cmp_lt_i32_e64 s[0:1], 2, v164
	v_readlane_b32 s11, v253, 23
	v_readlane_b32 s12, v253, 24
	v_cndmask_b32_e64 v116, 0, 1.0, s[0:1]
	s_waitcnt lgkmcnt(3)
	v_pk_mul_f32 v[186:187], v[116:117], v[170:171] op_sel_hi:[0,1]
	v_pk_mul_f32 v[188:189], v[116:117], v[168:169] op_sel_hi:[0,1]
	ds_read_b128 v[168:171], v115 offset:512
	v_cmp_lt_i32_e64 s[0:1], 1, v164
	s_waitcnt lgkmcnt(1)
	v_pk_mul_f32 v[190:191], v[116:117], v[182:183] op_sel_hi:[0,1]
	v_pk_mul_f32 v[192:193], v[116:117], v[180:181] op_sel_hi:[0,1]
	ds_read_b128 v[180:183], v115 offset:528
	v_cndmask_b32_e64 v116, 0, 1.0, s[0:1]
	s_waitcnt lgkmcnt(1)
	v_pk_mul_f32 v[194:195], v[116:117], v[170:171] op_sel_hi:[0,1]
	v_pk_mul_f32 v[196:197], v[116:117], v[168:169] op_sel_hi:[0,1]
	ds_read_b128 v[168:171], v115 offset:1024
	s_waitcnt lgkmcnt(1)
	v_pk_mul_f32 v[198:199], v[116:117], v[182:183] op_sel_hi:[0,1]
	ds_read_b128 v[182:185], v115 offset:1040
	v_pk_mul_f32 v[222:223], v[116:117], v[180:181] op_sel_hi:[0,1]
	v_cndmask_b32_e64 v116, 0, 1.0, s[58:59]
	s_waitcnt lgkmcnt(1)
	v_pk_mul_f32 v[224:225], v[116:117], v[170:171] op_sel_hi:[0,1]
	v_pk_mul_f32 v[226:227], v[116:117], v[168:169] op_sel_hi:[0,1]
	ds_read_b128 v[168:171], v115 offset:1536
	v_cmp_lt_i32_e64 s[0:1], -1, v164
	v_pk_fma_f32 v[172:173], v[188:189], v[230:231], v[172:173]
	v_lshlrev_b32_e32 v188, 16, v34
	v_and_b32_e32 v189, 0xffff0000, v34
	s_waitcnt lgkmcnt(1)
	v_pk_mul_f32 v[184:185], v[116:117], v[184:185] op_sel_hi:[0,1]
	v_pk_mul_f32 v[228:229], v[116:117], v[182:183] op_sel_hi:[0,1]
	v_cndmask_b32_e64 v116, 0, 1.0, s[0:1]
	v_pk_fma_f32 v[172:173], v[196:197], v[188:189], v[172:173]
	v_lshlrev_b32_e32 v188, 16, v46
	v_and_b32_e32 v189, 0xffff0000, v46
	ds_read_b128 v[180:183], v115 offset:1552
	s_waitcnt lgkmcnt(1)
	v_pk_mul_f32 v[168:169], v[116:117], v[168:169] op_sel_hi:[0,1]
	v_pk_fma_f32 v[172:173], v[226:227], v[188:189], v[172:173]
	v_lshlrev_b32_e32 v188, 16, v42
	v_and_b32_e32 v189, 0xffff0000, v42
	v_pk_fma_f32 v[168:169], v[168:169], v[188:189], v[172:173]
	v_pk_mul_f32 v[170:171], v[116:117], v[170:171] op_sel_hi:[0,1]
	v_mul_f32_e32 v38, 0xbfb8aa3b, v169
	v_exp_f32_e32 v38, v38
	s_waitcnt lgkmcnt(0)
	v_pk_mul_f32 v[182:183], v[116:117], v[182:183] op_sel_hi:[0,1]
	v_pk_mul_f32 v[172:173], v[116:117], v[180:181] op_sel_hi:[0,1]
	v_lshlrev_b32_e32 v46, 16, v47
	v_add_f32_e32 v116, 1.0, v38
	v_lshlrev_b32_e32 v38, 16, v39
	v_and_b32_e32 v39, 0xffff0000, v39
	v_pk_fma_f32 v[38:39], v[186:187], v[38:39], v[174:175]
	v_lshlrev_b32_e32 v174, 16, v35
	v_and_b32_e32 v175, 0xffff0000, v35
	v_pk_fma_f32 v[38:39], v[194:195], v[174:175], v[38:39]
	v_and_b32_e32 v47, 0xffff0000, v47
	v_pk_fma_f32 v[38:39], v[224:225], v[46:47], v[38:39]
	v_lshlrev_b32_e32 v42, 16, v43
	v_and_b32_e32 v43, 0xffff0000, v43
	v_lshlrev_b32_e32 v46, 16, v40
	v_and_b32_e32 v47, 0xffff0000, v40
	v_pk_fma_f32 v[38:39], v[170:171], v[42:43], v[38:39]
	v_pk_fma_f32 v[46:47], v[192:193], v[46:47], v[176:177]
	v_lshlrev_b32_e32 v170, 16, v36
	v_and_b32_e32 v171, 0xffff0000, v36
	v_pk_fma_f32 v[46:47], v[222:223], v[170:171], v[46:47]
	v_lshlrev_b32_e32 v170, 16, v48
	v_and_b32_e32 v171, 0xffff0000, v48
	v_pk_fma_f32 v[46:47], v[228:229], v[170:171], v[46:47]
	v_lshlrev_b32_e32 v170, 16, v44
	v_and_b32_e32 v171, 0xffff0000, v44
	v_pk_fma_f32 v[46:47], v[172:173], v[170:171], v[46:47]
	v_mul_f32_e32 v35, 0xbfb8aa3b, v38
	v_mul_f32_e32 v40, 0xbfb8aa3b, v47
	v_exp_f32_e32 v40, v40
	v_exp_f32_e32 v42, v35
	v_mul_f32_e32 v35, 0xbfb8aa3b, v39
	v_exp_f32_e32 v43, v35
	v_rcp_f32_e32 v35, v116
	v_add_f32_e32 v116, 1.0, v40
	v_lshlrev_b32_e32 v40, 16, v41
	v_and_b32_e32 v41, 0xffff0000, v41
	v_pk_fma_f32 v[40:41], v[190:191], v[40:41], v[178:179]
	v_lshlrev_b32_e32 v170, 16, v37
	v_and_b32_e32 v171, 0xffff0000, v37
	v_pk_fma_f32 v[40:41], v[198:199], v[170:171], v[40:41]
	v_lshlrev_b32_e32 v48, 16, v49
	v_and_b32_e32 v49, 0xffff0000, v49
; DI float silu(float x) { return x * __builtin_amdgcn_rcpf(1.f + __expf(-x)); }
; DI u32x4 pack8(const float (&f)[8]) { u32x4 r; r[0] = pk2(f[0], f[1]); r[1] = pk2(f[2], f[3]); r[2] = pk2(f[4], f[5]); r[3] = pk2(f[6], f[7]); return r; }
; DI void ssd_cb_phase(const bf16_t* P, bf16_t* BT, bf16_t* Cc, bf16_t* CB, const float* dt, float* acs,
;                      const float* cw, const float* cb, const float* A_log, char* lds) {
;     ...
; #pragma unroll
;     for (int j = 0; j < 4; ++j) {
;       const int q = tid + 512 * j, l = q >> 4, cch = q & 15;
;       float v[8];
;       { const f32x4 b0 = *(const f32x4*)(sW + 640 + 512 + cch * 8), b1 = *(const f32x4*)(sW + 640 + 512 + cch * 8 + 4);
;         v[0] = b0[0]; v[1] = b0[1]; v[2] = b0[2]; v[3] = b0[3]; v[4] = b1[0]; v[5] = b1[1]; v[6] = b1[2]; v[7] = b1[3]; }
; #pragma unroll
;       for (int kk = 0; kk < 4; ++kk) {
;         float f[8]; unpack8(raw[j][kk], f);
;         const float ok = (tin0 + l - 3 + kk >= 0) ? 1.f : 0.f;
;         const f32x4 w0 = *(const f32x4*)(sW + 640 + kk * 128 + cch * 8) * ok, w1 = *(const f32x4*)(sW + 640 + kk * 128 + cch * 8 + 4) * ok;
;         v[0] += w0[0] * f[0]; v[1] += w0[1] * f[1]; v[2] += w0[2] * f[2]; v[3] += w0[3] * f[3];
;         v[4] += w1[0] * f[4]; v[5] += w1[1] * f[5]; v[6] += w1[2] * f[6]; v[7] += w1[3] * f[7];
;       }
; #pragma unroll
;       for (int e = 0; e < 8; ++e) v[e] = silu(v[e]);
;       const u32x4 pk = pack8(v);
;       *(u32x4*)(sC + swz128(l, cch)) = pk;
;       *(u32x4*)(Cci + l * 128 + cch * 8) = pk;
;     }
	v_pk_fma_f32 v[40:41], v[184:185], v[48:49], v[40:41]
	v_lshlrev_b32_e32 v44, 16, v45
	v_and_b32_e32 v45, 0xffff0000, v45
	v_pk_fma_f32 v[40:41], v[182:183], v[44:45], v[40:41]
	v_mul_f32_e32 v34, 0xbfb8aa3b, v168
	v_mul_f32_e32 v37, 0xbfb8aa3b, v40
	v_mul_f32_e32 v36, 0xbfb8aa3b, v46
	v_exp_f32_e32 v44, v37
	v_mul_f32_e32 v37, 0xbfb8aa3b, v41
	v_exp_f32_e32 v34, v34
	v_exp_f32_e32 v36, v36
	v_exp_f32_e32 v45, v37
	v_add_f32_e32 v42, 1.0, v42
	v_add_f32_e32 v34, 1.0, v34
	v_add_f32_e32 v43, 1.0, v43
	v_add_f32_e32 v36, 1.0, v36
	v_add_f32_e32 v44, 1.0, v44
	v_add_f32_e32 v45, 1.0, v45
	v_rcp_f32_e32 v34, v34
	v_rcp_f32_e32 v42, v42
	v_rcp_f32_e32 v43, v43
	v_rcp_f32_e32 v36, v36
	v_rcp_f32_e32 v37, v116
	v_rcp_f32_e32 v44, v44
	v_rcp_f32_e32 v45, v45
	v_pk_mul_f32 v[34:35], v[168:169], v[34:35]
	v_pk_mul_f32 v[38:39], v[38:39], v[42:43]
	v_pk_mul_f32 v[36:37], v[46:47], v[36:37]
	v_pk_mul_f32 v[40:41], v[40:41], v[44:45]
	v_cvt_pk_bf16_f32 v34, v34, v35
	v_cvt_pk_bf16_f32 v35, v38, v39
	v_cvt_pk_bf16_f32 v36, v36, v37
	v_cvt_pk_bf16_f32 v37, v40, v41
	v_lshl_add_u64 v[38:39], v[92:93], 1, v[112:113]
	ds_write_b128 v160, v[34:37] offset:32768
	global_store_dwordx4 v[38:39], v[34:37], off
	ds_read_b128 v[34:37], v115
	ds_read_b128 v[38:41], v73
	ds_read_b128 v[42:45], v73 offset:16
	ds_read_b128 v[46:49], v115 offset:16
	v_cmp_lt_i32_e64 s[0:1], 2, v165
	ds_read_b128 v[168:171], v115 offset:1040
	v_lshlrev_b32_e32 v164, 16, v54
	v_cndmask_b32_e64 v116, 0, 1.0, s[0:1]
	s_waitcnt lgkmcnt(4)
	v_pk_mul_f32 v[172:173], v[116:117], v[36:37] op_sel_hi:[0,1]
	v_pk_mul_f32 v[174:175], v[116:117], v[34:35] op_sel_hi:[0,1]
	ds_read_b128 v[34:37], v115 offset:512
	v_cmp_lt_i32_e64 s[0:1], 1, v165
	s_waitcnt lgkmcnt(2)
	v_pk_mul_f32 v[176:177], v[116:117], v[48:49] op_sel_hi:[0,1]
	v_pk_mul_f32 v[178:179], v[116:117], v[46:47] op_sel_hi:[0,1]
	ds_read_b128 v[46:49], v115 offset:528
	v_cndmask_b32_e64 v116, 0, 1.0, s[0:1]
	s_waitcnt lgkmcnt(1)
	v_pk_mul_f32 v[180:181], v[116:117], v[36:37] op_sel_hi:[0,1]
	v_pk_mul_f32 v[182:183], v[116:117], v[34:35] op_sel_hi:[0,1]
	ds_read_b128 v[34:37], v115 offset:1024
	s_waitcnt lgkmcnt(1)
	v_pk_mul_f32 v[186:187], v[116:117], v[46:47] op_sel_hi:[0,1]
	v_cndmask_b32_e64 v46, 0, 1.0, s[60:61]
	v_cmp_lt_i32_e64 s[0:1], -1, v165
	v_and_b32_e32 v165, 0xffff0000, v54
	s_waitcnt lgkmcnt(0)
	v_pk_mul_f32 v[188:189], v[46:47], v[36:37] op_sel_hi:[0,1]
	v_pk_mul_f32 v[190:191], v[46:47], v[34:35] op_sel_hi:[0,1]
	ds_read_b128 v[34:37], v115 offset:1536
	v_pk_fma_f32 v[38:39], v[174:175], v[164:165], v[38:39]
	v_lshlrev_b32_e32 v164, 16, v50
	v_and_b32_e32 v165, 0xffff0000, v50
	v_pk_mul_f32 v[184:185], v[116:117], v[48:49] op_sel_hi:[0,1]
	v_cndmask_b32_e64 v116, 0, 1.0, s[0:1]
	v_pk_fma_f32 v[38:39], v[182:183], v[164:165], v[38:39]
	v_lshlrev_b32_e32 v164, 16, v62
	v_and_b32_e32 v165, 0xffff0000, v62
	v_pk_mul_f32 v[170:171], v[46:47], v[170:171] op_sel_hi:[0,1]
	v_pk_mul_f32 v[168:169], v[46:47], v[168:169] op_sel_hi:[0,1]
	ds_read_b128 v[46:49], v115 offset:1552
	s_waitcnt lgkmcnt(1)
	v_pk_mul_f32 v[34:35], v[116:117], v[34:35] op_sel_hi:[0,1]
	v_pk_fma_f32 v[38:39], v[190:191], v[164:165], v[38:39]
	v_lshlrev_b32_e32 v164, 16, v58
	v_and_b32_e32 v165, 0xffff0000, v58
	v_pk_fma_f32 v[34:35], v[34:35], v[164:165], v[38:39]
	v_pk_mul_f32 v[36:37], v[116:117], v[36:37] op_sel_hi:[0,1]
	v_mul_f32_e32 v38, 0xbfb8aa3b, v34
	v_exp_f32_e32 v50, v38
	v_mul_f32_e32 v38, 0xbfb8aa3b, v35
	v_exp_f32_e32 v54, v38
	s_waitcnt lgkmcnt(0)
	v_pk_mul_f32 v[38:39], v[116:117], v[46:47] op_sel_hi:[0,1]
	v_add_f32_e32 v46, 1.0, v50
	v_lshlrev_b32_e32 v50, 16, v51
	v_add_f32_e32 v47, 1.0, v54
	v_lshlrev_b32_e32 v54, 16, v55
	v_and_b32_e32 v55, 0xffff0000, v55
	v_pk_fma_f32 v[40:41], v[172:173], v[54:55], v[40:41]
	v_and_b32_e32 v51, 0xffff0000, v51
	v_pk_fma_f32 v[40:41], v[180:181], v[50:51], v[40:41]
	v_lshlrev_b32_e32 v50, 16, v63
	v_and_b32_e32 v51, 0xffff0000, v63
	v_pk_fma_f32 v[40:41], v[188:189], v[50:51], v[40:41]
	v_lshlrev_b32_e32 v50, 16, v59
	v_and_b32_e32 v51, 0xffff0000, v59
	v_pk_fma_f32 v[36:37], v[36:37], v[50:51], v[40:41]
	v_lshlrev_b32_e32 v50, 16, v56
	v_and_b32_e32 v51, 0xffff0000, v56
	v_pk_fma_f32 v[42:43], v[178:179], v[50:51], v[42:43]
	v_lshlrev_b32_e32 v50, 16, v52
	v_and_b32_e32 v51, 0xffff0000, v52
	v_pk_fma_f32 v[42:43], v[186:187], v[50:51], v[42:43]
	v_lshlrev_b32_e32 v50, 16, v64
	v_and_b32_e32 v51, 0xffff0000, v64
	v_pk_fma_f32 v[42:43], v[168:169], v[50:51], v[42:43]
	v_lshlrev_b32_e32 v50, 16, v60
	v_and_b32_e32 v51, 0xffff0000, v60
	v_pk_fma_f32 v[38:39], v[38:39], v[50:51], v[42:43]
	v_lshlrev_b32_e32 v50, 16, v57
	v_and_b32_e32 v51, 0xffff0000, v57
	v_pk_fma_f32 v[44:45], v[176:177], v[50:51], v[44:45]
	v_lshlrev_b32_e32 v50, 16, v53
	v_and_b32_e32 v51, 0xffff0000, v53
	v_pk_fma_f32 v[44:45], v[184:185], v[50:51], v[44:45]
	v_lshlrev_b32_e32 v50, 16, v65
	v_and_b32_e32 v51, 0xffff0000, v65
	v_pk_mul_f32 v[48:49], v[116:117], v[48:49] op_sel_hi:[0,1]
	v_pk_fma_f32 v[44:45], v[170:171], v[50:51], v[44:45]
	v_lshlrev_b32_e32 v50, 16, v61
	v_and_b32_e32 v51, 0xffff0000, v61
	v_pk_fma_f32 v[44:45], v[48:49], v[50:51], v[44:45]
	v_mul_f32_e32 v40, 0xbfb8aa3b, v36
	v_mul_f32_e32 v41, 0xbfb8aa3b, v37
	v_mul_f32_e32 v42, 0xbfb8aa3b, v38
	v_mul_f32_e32 v43, 0xbfb8aa3b, v39
	v_mul_f32_e32 v48, 0xbfb8aa3b, v44
	v_mul_f32_e32 v49, 0xbfb8aa3b, v45
	v_exp_f32_e32 v40, v40
	v_exp_f32_e32 v41, v41
	v_exp_f32_e32 v42, v42
	v_exp_f32_e32 v43, v43
	v_exp_f32_e32 v48, v48
	v_exp_f32_e32 v49, v49
	v_add_f32_e32 v40, 1.0, v40
	v_add_f32_e32 v41, 1.0, v41
	v_add_f32_e32 v42, 1.0, v42
	v_add_f32_e32 v43, 1.0, v43
	v_add_f32_e32 v48, 1.0, v48
	v_add_f32_e32 v49, 1.0, v49
	v_rcp_f32_e32 v46, v46
	v_rcp_f32_e32 v47, v47
	v_rcp_f32_e32 v40, v40
	v_rcp_f32_e32 v41, v41
	v_rcp_f32_e32 v42, v42
	v_rcp_f32_e32 v43, v43
	v_rcp_f32_e32 v48, v48
	v_rcp_f32_e32 v49, v49
	v_pk_mul_f32 v[34:35], v[34:35], v[46:47]
	v_pk_mul_f32 v[36:37], v[36:37], v[40:41]
	v_pk_mul_f32 v[38:39], v[38:39], v[42:43]
	v_pk_mul_f32 v[40:41], v[44:45], v[48:49]
	v_cvt_pk_bf16_f32 v34, v34, v35
	v_cvt_pk_bf16_f32 v35, v36, v37
	v_cvt_pk_bf16_f32 v36, v38, v39
	v_cvt_pk_bf16_f32 v37, v40, v41
	v_lshl_add_u64 v[38:39], v[94:95], 1, v[112:113]
	ds_write_b128 v161, v[34:37] offset:32768
	global_store_dwordx4 v[38:39], v[34:37], off
	ds_read_b128 v[34:37], v115
	ds_read_b128 v[38:41], v73
	ds_read_b128 v[42:45], v73 offset:16
	ds_read_b128 v[46:49], v115 offset:16
	v_cmp_lt_i32_e64 s[0:1], 2, v166
	v_readlane_b32 s13, v253, 25
	v_readlane_b32 s14, v253, 26
	v_cndmask_b32_e64 v50, 0, 1.0, s[0:1]
	s_waitcnt lgkmcnt(3)
; DI float silu(float x) { return x * __builtin_amdgcn_rcpf(1.f + __expf(-x)); }
; DI u32x4 pack8(const float (&f)[8]) { u32x4 r; r[0] = pk2(f[0], f[1]); r[1] = pk2(f[2], f[3]); r[2] = pk2(f[4], f[5]); r[3] = pk2(f[6], f[7]); return r; }
; DI void ssd_cb_phase(const bf16_t* P, bf16_t* BT, bf16_t* Cc, bf16_t* CB, const float* dt, float* acs,
;                      const float* cw, const float* cb, const float* A_log, char* lds) {
;     ...
; #pragma unroll
;     for (int j = 0; j < 4; ++j) {
;       const int q = tid + 512 * j, l = q >> 4, cch = q & 15;
;       float v[8];
;       { const f32x4 b0 = *(const f32x4*)(sW + 640 + 512 + cch * 8), b1 = *(const f32x4*)(sW + 640 + 512 + cch * 8 + 4);
;         v[0] = b0[0]; v[1] = b0[1]; v[2] = b0[2]; v[3] = b0[3]; v[4] = b1[0]; v[5] = b1[1]; v[6] = b1[2]; v[7] = b1[3]; }
; #pragma unroll
;       for (int kk = 0; kk < 4; ++kk) {
;         float f[8]; unpack8(raw[j][kk], f);
;         const float ok = (tin0 + l - 3 + kk >= 0) ? 1.f : 0.f;
;         const f32x4 w0 = *(const f32x4*)(sW + 640 + kk * 128 + cch * 8) * ok, w1 = *(const f32x4*)(sW + 640 + kk * 128 + cch * 8 + 4) * ok;
;         v[0] += w0[0] * f[0]; v[1] += w0[1] * f[1]; v[2] += w0[2] * f[2]; v[3] += w0[3] * f[3];
;         v[4] += w1[0] * f[4]; v[5] += w1[1] * f[5]; v[6] += w1[2] * f[6]; v[7] += w1[3] * f[7];
;       }
; #pragma unroll
;       for (int e = 0; e < 8; ++e) v[e] = silu(v[e]);
;       const u32x4 pk = pack8(v);
;       *(u32x4*)(sC + swz128(l, cch)) = pk;
;       *(u32x4*)(Cci + l * 128 + cch * 8) = pk;
;     }
	v_pk_mul_f32 v[52:53], v[50:51], v[36:37] op_sel_hi:[0,1]
	v_pk_mul_f32 v[54:55], v[50:51], v[34:35] op_sel_hi:[0,1]
	ds_read_b128 v[34:37], v115 offset:512
	v_cmp_lt_i32_e64 s[0:1], 1, v166
	s_waitcnt lgkmcnt(1)
	v_pk_mul_f32 v[56:57], v[50:51], v[48:49] op_sel_hi:[0,1]
	v_pk_mul_f32 v[58:59], v[50:51], v[46:47] op_sel_hi:[0,1]
	ds_read_b128 v[46:49], v115 offset:528
	v_cndmask_b32_e64 v60, 0, 1.0, s[0:1]
	s_waitcnt lgkmcnt(1)
	v_pk_mul_f32 v[62:63], v[60:61], v[36:37] op_sel_hi:[0,1]
	v_pk_mul_f32 v[64:65], v[60:61], v[34:35] op_sel_hi:[0,1]
	ds_read_b128 v[34:37], v115 offset:1024
	s_waitcnt lgkmcnt(1)
	v_pk_mul_f32 v[164:165], v[60:61], v[48:49] op_sel_hi:[0,1]
	v_pk_mul_f32 v[60:61], v[60:61], v[46:47] op_sel_hi:[0,1]
	v_cndmask_b32_e64 v46, 0, 1.0, s[62:63]
	ds_read_b128 v[48:51], v115 offset:1040
	s_waitcnt lgkmcnt(1)
	v_pk_mul_f32 v[168:169], v[46:47], v[36:37] op_sel_hi:[0,1]
	v_pk_mul_f32 v[170:171], v[46:47], v[34:35] op_sel_hi:[0,1]
	ds_read_b128 v[34:37], v115 offset:1536
	v_cmp_lt_i32_e64 s[0:1], -1, v166
	v_lshlrev_b32_e32 v166, 16, v22
	v_pk_fma_f32 v[38:39], v[54:55], v[166:167], v[38:39]
	s_waitcnt vmcnt(16)
	v_lshlrev_b32_e32 v54, 16, v18
	v_and_b32_e32 v55, 0xffff0000, v18
	v_cndmask_b32_e64 v116, 0, 1.0, s[0:1]
	v_pk_fma_f32 v[38:39], v[64:65], v[54:55], v[38:39]
	s_waitcnt vmcnt(15)
	v_lshlrev_b32_e32 v54, 16, v30
	v_and_b32_e32 v55, 0xffff0000, v30
	s_waitcnt lgkmcnt(1)
	v_pk_mul_f32 v[50:51], v[46:47], v[50:51] op_sel_hi:[0,1]
	v_pk_mul_f32 v[172:173], v[46:47], v[48:49] op_sel_hi:[0,1]
	ds_read_b128 v[46:49], v115 offset:1552
	s_waitcnt lgkmcnt(1)
	v_pk_mul_f32 v[34:35], v[116:117], v[34:35] op_sel_hi:[0,1]
	v_pk_fma_f32 v[38:39], v[170:171], v[54:55], v[38:39]
	s_waitcnt vmcnt(14)
	v_lshlrev_b32_e32 v54, 16, v26
	v_and_b32_e32 v55, 0xffff0000, v26
	v_pk_fma_f32 v[34:35], v[34:35], v[54:55], v[38:39]
	s_waitcnt lgkmcnt(0)
	v_pk_mul_f32 v[38:39], v[116:117], v[46:47] op_sel_hi:[0,1]
	v_mul_f32_e32 v22, 0xbfb8aa3b, v35
	v_exp_f32_e32 v22, v22
	v_lshlrev_b32_e32 v30, 16, v31
	v_and_b32_e32 v31, 0xffff0000, v31
	v_pk_mul_f32 v[36:37], v[116:117], v[36:37] op_sel_hi:[0,1]
	v_add_f32_e32 v46, 1.0, v22
	v_lshlrev_b32_e32 v22, 16, v23
	v_and_b32_e32 v23, 0xffff0000, v23
	v_pk_fma_f32 v[22:23], v[52:53], v[22:23], v[40:41]
	v_lshlrev_b32_e32 v40, 16, v19
	v_and_b32_e32 v41, 0xffff0000, v19
	v_pk_fma_f32 v[22:23], v[62:63], v[40:41], v[22:23]
	v_lshlrev_b32_e32 v26, 16, v27
	v_pk_fma_f32 v[22:23], v[168:169], v[30:31], v[22:23]
	v_and_b32_e32 v27, 0xffff0000, v27
	v_lshlrev_b32_e32 v30, 16, v24
	v_and_b32_e32 v31, 0xffff0000, v24
	v_pk_fma_f32 v[22:23], v[36:37], v[26:27], v[22:23]
	v_pk_fma_f32 v[30:31], v[58:59], v[30:31], v[42:43]
	v_lshlrev_b32_e32 v36, 16, v20
	v_and_b32_e32 v37, 0xffff0000, v20
	v_pk_fma_f32 v[30:31], v[60:61], v[36:37], v[30:31]
	v_lshlrev_b32_e32 v36, 16, v32
	v_and_b32_e32 v37, 0xffff0000, v32
	v_pk_fma_f32 v[30:31], v[172:173], v[36:37], v[30:31]
	v_lshlrev_b32_e32 v36, 16, v28
	v_and_b32_e32 v37, 0xffff0000, v28
	v_pk_fma_f32 v[30:31], v[38:39], v[36:37], v[30:31]
	v_lshlrev_b32_e32 v36, 16, v21
	v_mul_f32_e32 v24, 0xbfb8aa3b, v31
	v_exp_f32_e32 v24, v24
	v_and_b32_e32 v37, 0xffff0000, v21
	v_lshlrev_b32_e32 v32, 16, v33
	v_and_b32_e32 v33, 0xffff0000, v33
	v_add_f32_e32 v38, 1.0, v24
	v_lshlrev_b32_e32 v24, 16, v25
	v_and_b32_e32 v25, 0xffff0000, v25
	v_pk_fma_f32 v[24:25], v[56:57], v[24:25], v[44:45]
	v_pk_mul_f32 v[48:49], v[116:117], v[48:49] op_sel_hi:[0,1]
	v_pk_fma_f32 v[24:25], v[164:165], v[36:37], v[24:25]
	v_lshlrev_b32_e32 v28, 16, v29
	v_pk_fma_f32 v[24:25], v[50:51], v[32:33], v[24:25]
	v_and_b32_e32 v29, 0xffff0000, v29
	v_pk_fma_f32 v[24:25], v[48:49], v[28:29], v[24:25]
	v_mul_f32_e32 v19, 0xbfb8aa3b, v22
	v_mul_f32_e32 v21, 0xbfb8aa3b, v24
	v_mul_f32_e32 v18, 0xbfb8aa3b, v34
	v_exp_f32_e32 v26, v19
	v_mul_f32_e32 v19, 0xbfb8aa3b, v23
	v_mul_f32_e32 v20, 0xbfb8aa3b, v30
	v_exp_f32_e32 v28, v21
	v_mul_f32_e32 v21, 0xbfb8aa3b, v25
	v_exp_f32_e32 v18, v18
	v_exp_f32_e32 v27, v19
	v_exp_f32_e32 v20, v20
	v_exp_f32_e32 v29, v21
	v_add_f32_e32 v18, 1.0, v18
	v_add_f32_e32 v26, 1.0, v26
	v_add_f32_e32 v27, 1.0, v27
	v_add_f32_e32 v20, 1.0, v20
	v_add_f32_e32 v28, 1.0, v28
	v_add_f32_e32 v29, 1.0, v29
	v_rcp_f32_e32 v18, v18
	v_rcp_f32_e32 v19, v46
	v_rcp_f32_e32 v26, v26
	v_rcp_f32_e32 v27, v27
	v_rcp_f32_e32 v20, v20
	v_rcp_f32_e32 v21, v38
	v_rcp_f32_e32 v28, v28
	v_rcp_f32_e32 v29, v29
	v_pk_mul_f32 v[18:19], v[34:35], v[18:19]
	v_pk_mul_f32 v[22:23], v[22:23], v[26:27]
	v_pk_mul_f32 v[20:21], v[30:31], v[20:21]
	v_pk_mul_f32 v[24:25], v[24:25], v[28:29]
	v_cvt_pk_bf16_f32 v18, v18, v19
	v_cvt_pk_bf16_f32 v19, v22, v23
	v_cvt_pk_bf16_f32 v20, v20, v21
	v_cvt_pk_bf16_f32 v21, v24, v25
	v_lshl_add_u64 v[22:23], v[96:97], 1, v[112:113]
	ds_write_b128 v162, v[18:21] offset:32768
	global_store_dwordx4 v[22:23], v[18:21], off
	ds_read_b128 v[18:21], v115
	ds_read_b128 v[22:25], v73
	ds_read_b128 v[26:29], v73 offset:16
	ds_read_b128 v[30:33], v115 offset:16
	v_cmp_lt_i32_e64 s[0:1], 2, v114
	s_waitcnt vmcnt(6)
	v_lshlrev_b32_e32 v60, 16, v6
	v_and_b32_e32 v61, 0xffff0000, v6
	v_cndmask_b32_e64 v34, 0, 1.0, s[0:1]
	s_waitcnt lgkmcnt(3)
	v_pk_mul_f32 v[36:37], v[34:35], v[20:21] op_sel_hi:[0,1]
	v_pk_mul_f32 v[38:39], v[34:35], v[18:19] op_sel_hi:[0,1]
	ds_read_b128 v[18:21], v115 offset:512
	v_cmp_lt_i32_e64 s[0:1], 1, v114
	s_waitcnt lgkmcnt(1)
	v_pk_mul_f32 v[40:41], v[34:35], v[32:33] op_sel_hi:[0,1]
	v_pk_mul_f32 v[42:43], v[34:35], v[30:31] op_sel_hi:[0,1]
	ds_read_b128 v[30:33], v115 offset:528
	v_cndmask_b32_e64 v44, 0, 1.0, s[0:1]
	s_waitcnt lgkmcnt(1)
; DI float silu(float x) { return x * __builtin_amdgcn_rcpf(1.f + __expf(-x)); }
; DI u32x4 pack8(const float (&f)[8]) { u32x4 r; r[0] = pk2(f[0], f[1]); r[1] = pk2(f[2], f[3]); r[2] = pk2(f[4], f[5]); r[3] = pk2(f[6], f[7]); return r; }
; #define LDS_BARRIER() do { asm volatile("s_waitcnt lgkmcnt(0)" ::: "memory"); __builtin_amdgcn_s_barrier(); asm volatile("" ::: "memory"); } while (0)
; DI void ssd_cb_phase(const bf16_t* P, bf16_t* BT, bf16_t* Cc, bf16_t* CB, const float* dt, float* acs,
;                      const float* cw, const float* cb, const float* A_log, char* lds) {
;     ...
;     for (int j = 0; j < 4; ++j) {
;       const int q = tid + 512 * j, l = q >> 4, cch = q & 15;
;       float v[8];
;       { const f32x4 b0 = *(const f32x4*)(sW + 640 + 512 + cch * 8), b1 = *(const f32x4*)(sW + 640 + 512 + cch * 8 + 4);
;         v[0] = b0[0]; v[1] = b0[1]; v[2] = b0[2]; v[3] = b0[3]; v[4] = b1[0]; v[5] = b1[1]; v[6] = b1[2]; v[7] = b1[3]; }
; #pragma unroll
;       for (int kk = 0; kk < 4; ++kk) {
;         float f[8]; unpack8(raw[j][kk], f);
;         const float ok = (tin0 + l - 3 + kk >= 0) ? 1.f : 0.f;
;         const f32x4 w0 = *(const f32x4*)(sW + 640 + kk * 128 + cch * 8) * ok, w1 = *(const f32x4*)(sW + 640 + kk * 128 + cch * 8 + 4) * ok;
;         v[0] += w0[0] * f[0]; v[1] += w0[1] * f[1]; v[2] += w0[2] * f[2]; v[3] += w0[3] * f[3];
;         v[4] += w1[0] * f[4]; v[5] += w1[1] * f[5]; v[6] += w1[2] * f[6]; v[7] += w1[3] * f[7];
;       }
; #pragma unroll
;       for (int e = 0; e < 8; ++e) v[e] = silu(v[e]);
;       const u32x4 pk = pack8(v);
;       *(u32x4*)(sC + swz128(l, cch)) = pk;
;       *(u32x4*)(Cci + l * 128 + cch * 8) = pk;
;     }
;     {
;       const int hh = 8 * g + wave;
;       const float Ah = -__expf(A_log[hh]);
;       const int l0 = 2 * lane;
;       const float d0 = dt[(t0 + l0) * 32 + hh] * Ah, d1 = dt[(t0 + l0 + 1) * 32 + hh] * Ah;
;       float sc = d0 + d1;
; #pragma unroll
;       for (int o = 1; o < 64; o <<= 1) { const float v = __shfl_up(sc, o); if (lane >= o) sc += v; }
;       acs[(t0 + l0) * 32 + hh] = sc - d1;
;       acs[(t0 + l0 + 1) * 32 + hh] = sc;
;     }
;     LDS_BARRIER();
	v_pk_mul_f32 v[46:47], v[44:45], v[20:21] op_sel_hi:[0,1]
	v_pk_mul_f32 v[48:49], v[44:45], v[18:19] op_sel_hi:[0,1]
	ds_read_b128 v[18:21], v115 offset:1024
	s_waitcnt lgkmcnt(1)
	v_pk_mul_f32 v[50:51], v[44:45], v[32:33] op_sel_hi:[0,1]
	v_pk_mul_f32 v[44:45], v[44:45], v[30:31] op_sel_hi:[0,1]
	v_cndmask_b32_e64 v30, 0, 1.0, s[64:65]
	ds_read_b128 v[32:35], v115 offset:1040
	s_waitcnt lgkmcnt(1)
	v_pk_mul_f32 v[52:53], v[30:31], v[20:21] op_sel_hi:[0,1]
	v_pk_mul_f32 v[54:55], v[30:31], v[18:19] op_sel_hi:[0,1]
	ds_read_b128 v[18:21], v115 offset:1536
	v_cmp_lt_i32_e64 s[0:1], -1, v114
	v_pk_fma_f32 v[22:23], v[38:39], v[60:61], v[22:23]
	s_waitcnt vmcnt(5)
	v_lshlrev_b32_e32 v38, 16, v2
	v_and_b32_e32 v39, 0xffff0000, v2
	v_cndmask_b32_e64 v58, 0, 1.0, s[0:1]
	v_pk_fma_f32 v[22:23], v[48:49], v[38:39], v[22:23]
	s_waitcnt vmcnt(4)
	v_lshlrev_b32_e32 v38, 16, v14
	v_and_b32_e32 v39, 0xffff0000, v14
	s_waitcnt lgkmcnt(1)
	v_pk_mul_f32 v[34:35], v[30:31], v[34:35] op_sel_hi:[0,1]
	v_pk_mul_f32 v[56:57], v[30:31], v[32:33] op_sel_hi:[0,1]
	ds_read_b128 v[30:33], v115 offset:1552
	s_waitcnt lgkmcnt(1)
	v_pk_mul_f32 v[18:19], v[58:59], v[18:19] op_sel_hi:[0,1]
	v_pk_fma_f32 v[22:23], v[54:55], v[38:39], v[22:23]
	s_waitcnt vmcnt(3)
	v_lshlrev_b32_e32 v38, 16, v10
	v_and_b32_e32 v39, 0xffff0000, v10
	v_pk_fma_f32 v[18:19], v[18:19], v[38:39], v[22:23]
	s_waitcnt lgkmcnt(0)
	v_pk_mul_f32 v[22:23], v[58:59], v[30:31] op_sel_hi:[0,1]
	v_mul_f32_e32 v6, 0xbfb8aa3b, v19
	v_exp_f32_e32 v6, v6
	v_lshlrev_b32_e32 v14, 16, v15
	v_and_b32_e32 v15, 0xffff0000, v15
	v_pk_mul_f32 v[20:21], v[58:59], v[20:21] op_sel_hi:[0,1]
	v_add_f32_e32 v30, 1.0, v6
	v_lshlrev_b32_e32 v6, 16, v7
	v_and_b32_e32 v7, 0xffff0000, v7
	v_pk_fma_f32 v[6:7], v[36:37], v[6:7], v[24:25]
	v_lshlrev_b32_e32 v24, 16, v3
	v_and_b32_e32 v25, 0xffff0000, v3
	v_pk_fma_f32 v[6:7], v[46:47], v[24:25], v[6:7]
	v_lshlrev_b32_e32 v10, 16, v11
	v_pk_fma_f32 v[6:7], v[52:53], v[14:15], v[6:7]
	v_and_b32_e32 v11, 0xffff0000, v11
	v_lshlrev_b32_e32 v14, 16, v8
	v_and_b32_e32 v15, 0xffff0000, v8
	v_pk_fma_f32 v[6:7], v[20:21], v[10:11], v[6:7]
	v_pk_fma_f32 v[14:15], v[42:43], v[14:15], v[26:27]
	v_lshlrev_b32_e32 v20, 16, v4
	v_and_b32_e32 v21, 0xffff0000, v4
	v_pk_fma_f32 v[14:15], v[44:45], v[20:21], v[14:15]
	v_lshlrev_b32_e32 v20, 16, v16
	v_and_b32_e32 v21, 0xffff0000, v16
	v_pk_fma_f32 v[14:15], v[56:57], v[20:21], v[14:15]
	v_lshlrev_b32_e32 v20, 16, v12
	v_and_b32_e32 v21, 0xffff0000, v12
	v_pk_fma_f32 v[14:15], v[22:23], v[20:21], v[14:15]
	v_lshlrev_b32_e32 v20, 16, v5
	v_mul_f32_e32 v8, 0xbfb8aa3b, v15
	v_exp_f32_e32 v8, v8
	v_and_b32_e32 v21, 0xffff0000, v5
	v_lshlrev_b32_e32 v16, 16, v17
	v_and_b32_e32 v17, 0xffff0000, v17
	v_add_f32_e32 v22, 1.0, v8
	v_lshlrev_b32_e32 v8, 16, v9
	v_and_b32_e32 v9, 0xffff0000, v9
	v_pk_fma_f32 v[8:9], v[40:41], v[8:9], v[28:29]
	v_pk_mul_f32 v[32:33], v[58:59], v[32:33] op_sel_hi:[0,1]
	v_pk_fma_f32 v[8:9], v[50:51], v[20:21], v[8:9]
	v_lshlrev_b32_e32 v12, 16, v13
	v_pk_fma_f32 v[8:9], v[34:35], v[16:17], v[8:9]
	v_and_b32_e32 v13, 0xffff0000, v13
	v_pk_fma_f32 v[8:9], v[32:33], v[12:13], v[8:9]
	v_mul_f32_e32 v3, 0xbfb8aa3b, v6
	v_mul_f32_e32 v5, 0xbfb8aa3b, v8
	v_mul_f32_e32 v2, 0xbfb8aa3b, v18
	v_exp_f32_e32 v10, v3
	v_mul_f32_e32 v3, 0xbfb8aa3b, v7
	v_mul_f32_e32 v4, 0xbfb8aa3b, v14
	v_exp_f32_e32 v12, v5
	v_mul_f32_e32 v5, 0xbfb8aa3b, v9
	v_exp_f32_e32 v2, v2
	v_exp_f32_e32 v11, v3
	v_exp_f32_e32 v4, v4
	v_exp_f32_e32 v13, v5
	v_add_f32_e32 v2, 1.0, v2
	v_add_f32_e32 v10, 1.0, v10
	v_add_f32_e32 v11, 1.0, v11
	v_add_f32_e32 v4, 1.0, v4
	v_add_f32_e32 v12, 1.0, v12
	v_add_f32_e32 v13, 1.0, v13
	v_rcp_f32_e32 v2, v2
	v_rcp_f32_e32 v3, v30
	v_rcp_f32_e32 v10, v10
	v_rcp_f32_e32 v11, v11
	v_rcp_f32_e32 v4, v4
	v_rcp_f32_e32 v5, v22
	v_rcp_f32_e32 v12, v12
	v_rcp_f32_e32 v13, v13
	v_pk_mul_f32 v[2:3], v[18:19], v[2:3]
	v_pk_mul_f32 v[6:7], v[6:7], v[10:11]
	v_pk_mul_f32 v[4:5], v[14:15], v[4:5]
	v_pk_mul_f32 v[8:9], v[8:9], v[12:13]
	v_cvt_pk_bf16_f32 v2, v2, v3
	v_cvt_pk_bf16_f32 v3, v6, v7
	v_cvt_pk_bf16_f32 v4, v4, v5
	v_cvt_pk_bf16_f32 v5, v8, v9
	v_lshl_add_u64 v[6:7], v[98:99], 1, v[112:113]
	global_store_dwordx4 v[6:7], v[2:5], off
	v_lshl_add_u32 v6, s77, 3, v69
	v_ashrrev_i32_e32 v7, 31, v6
	v_lshl_add_u64 v[8:9], v[6:7], 2, s[30:31]
	global_load_dword v10, v[8:9], off
	v_mov_b32_e32 v9, s67
	v_or_b32_e32 v8, s66, v72
	v_lshlrev_b64 v[8:9], 5, v[8:9]
	v_lshl_add_u64 v[6:7], v[8:9], 0, v[6:7]
	v_lshlrev_b64 v[6:7], 2, v[6:7]
	v_lshl_add_u64 v[8:9], s[24:25], 0, v[6:7]
	global_load_dword v11, v[8:9], off
	s_nop 0
	global_load_dword v8, v[8:9], off offset:128
	v_add_u32_e32 v12, -1, v204
	ds_write_b128 v163, v[2:5] offset:32768
	v_add_u32_e32 v38, v132, v127
	v_add_u32_e32 v42, v132, v130
	v_readlane_b32 s15, v253, 27
	s_waitcnt vmcnt(2)
	v_mul_f32_e32 v9, 0x3fb8aa3b, v10
	v_exp_f32_e32 v9, v9
	s_waitcnt vmcnt(1)
	v_mul_f32_e32 v10, v9, v11
	v_and_b32_e32 v11, 64, v204
	v_cmp_lt_i32_e64 s[0:1], v12, v11
	s_waitcnt vmcnt(0)
	v_fma_f32 v10, v8, -v9, -v10
	v_cndmask_b32_e64 v12, v12, v204, s[0:1]
	v_lshlrev_b32_e32 v12, 2, v12
	ds_bpermute_b32 v12, v12, v10
	s_waitcnt lgkmcnt(0)
	v_add_f32_e32 v12, v10, v12
	v_cndmask_b32_e64 v10, v12, v10, s[42:43]
	v_add_u32_e32 v12, -2, v204
	v_cmp_lt_i32_e64 s[0:1], v12, v11
	s_nop 1
	v_cndmask_b32_e64 v12, v12, v204, s[0:1]
	v_lshlrev_b32_e32 v12, 2, v12
	ds_bpermute_b32 v12, v12, v10
	s_waitcnt lgkmcnt(0)
	v_add_f32_e32 v12, v10, v12
	v_cndmask_b32_e64 v10, v12, v10, s[44:45]
	v_add_u32_e32 v12, -4, v204
	v_cmp_lt_i32_e64 s[0:1], v12, v11
	s_nop 1
	v_cndmask_b32_e64 v12, v12, v204, s[0:1]
	v_lshlrev_b32_e32 v12, 2, v12
	ds_bpermute_b32 v12, v12, v10
	s_waitcnt lgkmcnt(0)
	v_add_f32_e32 v12, v10, v12
	v_cndmask_b32_e64 v10, v12, v10, s[46:47]
	v_add_u32_e32 v12, -8, v204
	v_cmp_lt_i32_e64 s[0:1], v12, v11
	s_nop 1
	v_cndmask_b32_e64 v12, v12, v204, s[0:1]
	v_lshlrev_b32_e32 v12, 2, v12
	ds_bpermute_b32 v12, v12, v10
	s_waitcnt lgkmcnt(0)
	v_add_f32_e32 v12, v10, v12
	v_cndmask_b32_e64 v10, v12, v10, s[48:49]
	v_add_u32_e32 v12, -16, v204
	v_cmp_lt_i32_e64 s[0:1], v12, v11
	s_nop 1
	v_cndmask_b32_e64 v12, v12, v204, s[0:1]
	v_lshlrev_b32_e32 v12, 2, v12
	ds_bpermute_b32 v12, v12, v10
	s_waitcnt lgkmcnt(0)
	v_add_f32_e32 v12, v10, v12
	v_cndmask_b32_e64 v10, v12, v10, s[50:51]
	v_subrev_u32_e32 v12, 32, v204
	v_cmp_lt_i32_e64 s[0:1], v12, v11
	s_nop 1
	v_cndmask_b32_e64 v11, v12, v204, s[0:1]
	v_lshlrev_b32_e32 v11, 2, v11
	ds_bpermute_b32 v11, v11, v10
	v_readlane_b32 s0, v252, 4
	v_readlane_b32 s1, v252, 5
	s_waitcnt lgkmcnt(0)
	v_add_f32_e32 v2, v10, v11
	v_cndmask_b32_e64 v4, v2, v10, s[52:53]
	v_fma_f32 v5, v8, v9, v4
	v_lshl_add_u64 v[2:3], s[26:27], 0, v[6:7]
	global_store_dword v[2:3], v5, off
	global_store_dword v[2:3], v4, off offset:128
	s_waitcnt lgkmcnt(0)
	s_barrier
; #define MFMA(a, b, c) __builtin_amdgcn_mfma_f32_32x32x16_bf16((a), (b), (c), 0, 0, 0)
; DI unsigned pk2(float lo, float hi) { f32x2 v = {lo, hi}; bf2_t r = __builtin_convertvector(v, bf2_t); return __builtin_bit_cast(unsigned, r); }
; #define LDS_BARRIER() do { asm volatile("s_waitcnt lgkmcnt(0)" ::: "memory"); __builtin_amdgcn_s_barrier(); asm volatile("" ::: "memory"); } while (0)
; DI void ssd_cb_phase(const bf16_t* P, bf16_t* BT, bf16_t* Cc, bf16_t* CB, const float* dt, float* acs,
;                      const float* cw, const float* cb, const float* A_log, char* lds) {
;     ...
;     const int lt = wave & 3, st0 = (wave >> 2) * 2;
;     f32x16 acc[2];
; #pragma unroll
;     for (int e = 0; e < 2; ++e)
; #pragma unroll
;       for (int i = 0; i < 16; ++i) acc[e][i] = 0.f;
; #pragma unroll
;     for (int kk = 0; kk < 8; ++kk) {
;       const bf16x8 yf = *(const bf16x8*)(sC + swz128(32 * lt + l31, 2 * kk + h));
; #pragma unroll
;       for (int e = 0; e < 2; ++e) {
;         const bf16x8 xf = *(const bf16x8*)(sB + swz128(32 * (st0 + e) + l31, 2 * kk + h));
;         acc[e] = MFMA(xf, yf, acc[e]);
;       }
;     }
;     const int l = 32 * lt + l31;
; #pragma unroll
;     for (int e = 0; e < 2; ++e)
; #pragma unroll
;       for (int gi = 0; gi < 4; ++gi) {
;         const int s = 32 * (st0 + e) + 8 * gi + 4 * h;
;         u32x2 ov; ov[0] = pk2(acc[e][4 * gi], acc[e][4 * gi + 1]); ov[1] = pk2(acc[e][4 * gi + 2], acc[e][4 * gi + 3]);
;         *(u32x2*)(CBi + l * 128 + s) = ov;
;       }
;     LDS_BARRIER();
;   }
	v_add_u32_e32 v2, v129, v127
	ds_read_b128 v[2:5], v2
	v_add_u32_e32 v6, v117, v128
	ds_read_b128 v[6:9], v6 offset:32768
	v_add_u32_e32 v10, v117, v131
	s_waitcnt lgkmcnt(0)
	v_mfma_f32_32x32x16_bf16 v[18:33], v[2:5], v[6:9], 0
	v_add_u32_e32 v2, v129, v130
	ds_read_b128 v[2:5], v2
	ds_read_b128 v[34:37], v10 offset:32768
	ds_read_b128 v[38:41], v38
	ds_read_b128 v[42:45], v42
	s_waitcnt lgkmcnt(3)
	v_mfma_f32_32x32x16_bf16 v[2:17], v[2:5], v[6:9], 0
	s_waitcnt lgkmcnt(1)
	v_mfma_f32_32x32x16_bf16 v[18:33], v[38:41], v[34:37], v[18:33]
	v_add_u32_e32 v38, v117, v133
	ds_read_b128 v[38:41], v38 offset:32768
	s_waitcnt lgkmcnt(1)
	v_mfma_f32_32x32x16_bf16 v[2:17], v[42:45], v[34:37], v[2:17]
	v_add_u32_e32 v34, v142, v127
	ds_read_b128 v[34:37], v34
	v_add_u32_e32 v42, v117, v143
	ds_read_b128 v[42:45], v42 offset:32768
	s_waitcnt lgkmcnt(1)
	v_mfma_f32_32x32x16_bf16 v[18:33], v[34:37], v[38:41], v[18:33]
	v_add_u32_e32 v34, v142, v130
	ds_read_b128 v[34:37], v34
	s_waitcnt lgkmcnt(0)
	v_mfma_f32_32x32x16_bf16 v[2:17], v[34:37], v[38:41], v[2:17]
	v_add_u32_e32 v38, v144, v130
	v_add_u32_e32 v34, v144, v127
	ds_read_b128 v[38:41], v38
	ds_read_b128 v[34:37], v34
	s_waitcnt lgkmcnt(1)
	v_mfma_f32_32x32x16_bf16 v[2:17], v[38:41], v[42:45], v[2:17]
	v_add_u32_e32 v38, v117, v145
	ds_read_b128 v[38:41], v38 offset:32768
	s_waitcnt lgkmcnt(1)
	v_mfma_f32_32x32x16_bf16 v[18:33], v[34:37], v[42:45], v[18:33]
	v_add_u32_e32 v34, v146, v127
	ds_read_b128 v[34:37], v34
	v_add_u32_e32 v42, v117, v147
	ds_read_b128 v[42:45], v42 offset:32768
	s_waitcnt lgkmcnt(1)
	v_mfma_f32_32x32x16_bf16 v[18:33], v[34:37], v[38:41], v[18:33]
	v_add_u32_e32 v34, v146, v130
	ds_read_b128 v[34:37], v34
	s_waitcnt lgkmcnt(0)
	v_mfma_f32_32x32x16_bf16 v[2:17], v[34:37], v[38:41], v[2:17]
	v_add_u32_e32 v38, v148, v130
	v_add_u32_e32 v34, v148, v127
	ds_read_b128 v[38:41], v38
	ds_read_b128 v[34:37], v34
	s_waitcnt lgkmcnt(1)
	v_mfma_f32_32x32x16_bf16 v[2:17], v[38:41], v[42:45], v[2:17]
	v_add_u32_e32 v38, v117, v149
	ds_read_b128 v[38:41], v38 offset:32768
	s_waitcnt lgkmcnt(1)
	v_mfma_f32_32x32x16_bf16 v[18:33], v[34:37], v[42:45], v[18:33]
	v_add_u32_e32 v34, v150, v127
	ds_read_b128 v[34:37], v34
	v_add_u32_e32 v42, v117, v151
	ds_read_b128 v[42:45], v42 offset:32768
	s_waitcnt lgkmcnt(1)
	v_mfma_f32_32x32x16_bf16 v[18:33], v[34:37], v[38:41], v[18:33]
	v_add_u32_e32 v34, v150, v130
	ds_read_b128 v[34:37], v34
	s_waitcnt lgkmcnt(0)
	v_mfma_f32_32x32x16_bf16 v[2:17], v[34:37], v[38:41], v[2:17]
	v_add_u32_e32 v34, v152, v127
	ds_read_b128 v[34:37], v34
	v_add_u32_e32 v38, v152, v130
	ds_read_b128 v[38:41], v38
	s_waitcnt lgkmcnt(1)
	v_mfma_f32_32x32x16_bf16 v[18:33], v[34:37], v[42:45], v[18:33]
	v_lshl_add_u64 v[34:35], v[74:75], 0, s[68:69]
	s_waitcnt lgkmcnt(0)
	v_mfma_f32_32x32x16_bf16 v[2:17], v[38:41], v[42:45], v[2:17]
	s_nop 8
	v_cvt_pk_bf16_f32 v18, v18, v19
	v_cvt_pk_bf16_f32 v19, v20, v21
	v_lshl_add_u64 v[20:21], v[100:101], 1, v[34:35]
	global_store_dwordx2 v[20:21], v[18:19], off
	v_cvt_pk_bf16_f32 v18, v22, v23
	v_cvt_pk_bf16_f32 v19, v24, v25
	global_store_dwordx2 v[20:21], v[18:19], off offset:16
	v_cvt_pk_bf16_f32 v18, v26, v27
	v_cvt_pk_bf16_f32 v19, v28, v29
	global_store_dwordx2 v[20:21], v[18:19], off offset:32
	v_cvt_pk_bf16_f32 v18, v30, v31
	v_cvt_pk_bf16_f32 v19, v32, v33
	v_cvt_pk_bf16_f32 v2, v2, v3
	v_cvt_pk_bf16_f32 v3, v4, v5
	v_lshl_add_u64 v[4:5], v[102:103], 1, v[34:35]
	global_store_dwordx2 v[20:21], v[18:19], off offset:48
	global_store_dwordx2 v[4:5], v[2:3], off
	v_cvt_pk_bf16_f32 v2, v6, v7
	v_cvt_pk_bf16_f32 v3, v8, v9
	global_store_dwordx2 v[4:5], v[2:3], off offset:16
	v_cvt_pk_bf16_f32 v2, v10, v11
	v_cvt_pk_bf16_f32 v3, v12, v13
	global_store_dwordx2 v[4:5], v[2:3], off offset:32
	v_cvt_pk_bf16_f32 v2, v14, v15
	v_cvt_pk_bf16_f32 v3, v16, v17
	global_store_dwordx2 v[4:5], v[2:3], off offset:48
	s_waitcnt lgkmcnt(0)
	s_barrier
	s_load_dword s0, s[0:1], 0x0
	s_waitcnt lgkmcnt(0)
	s_add_i32 s40, s0, s40
	s_cmpk_gt_i32 s40, 0x1ff
	s_cbranch_scc1 .LBB0_1135

; #define LDS_BARRIER() do { asm volatile("s_waitcnt lgkmcnt(0)" ::: "memory"); __builtin_amdgcn_s_barrier(); asm volatile("" ::: "memory"); } while (0)
; DI void ssd_cb_phase(const bf16_t* P, bf16_t* BT, bf16_t* Cc, bf16_t* CB, const float* dt, float* acs,
;                      const float* cw, const float* cb, const float* A_log, char* lds) {
;     ...
;       for (int kk = 0; kk < 4; ++kk) raw[j][kk] = *(const u32x4*)(P + (t0 + lb - ((tin0 + lb - 3 + kk >= 0) ? (3 - kk) : 0)) * 5120 + 2048 + 2048 + g * 128 + cb8 * 8);
;     }
;     for (int q = tid; q < 1280; q += 512) { const int which = q / 640, r = q % 640, kk = r >> 7, col = 2048 + which * 512 + g * 128 + (r & 127); sW[q] = (kk < 4) ? cw[kk * 3072 + col] : cb[col]; }
;     LDS_BARRIER();
.LBB0_1130:
	v_mul_hi_i32 v164, v112, s39
	v_lshrrev_b32_e32 v165, 31, v164
	v_ashrrev_i32_e32 v164, 8, v164
	v_add_u32_e32 v164, v164, v165
	v_mul_hi_i32 v165, v113, s39
	v_lshrrev_b32_e32 v166, 31, v165
	v_ashrrev_i32_e32 v165, 8, v165
	v_add_u32_e32 v165, v165, v166
	v_mul_lo_u32 v166, v164, s80
	v_mul_lo_u32 v167, v165, s80
	v_sub_u32_e32 v167, v113, v167
	v_sub_u32_e32 v166, v112, v166
	v_ashrrev_i32_e32 v168, 7, v167
	v_ashrrev_i32_e32 v169, 7, v166
	v_lshl_add_u32 v165, v165, 9, s68
	v_lshl_add_u32 v164, v164, 9, s41
	v_and_b32_e32 v167, 0x7f, v167
	v_and_b32_e32 v166, 0x7f, v166
	v_or_b32_e32 v165, v165, v167
	v_or_b32_e32 v164, v164, v166
	v_cmp_gt_i32_e64 s[0:1], 4, v169
	v_cmp_gt_i32_e64 s[58:59], 4, v168
	v_mul_lo_u32 v166, v169, s91
	v_mul_lo_u32 v167, v168, s91
	v_cndmask_b32_e64 v167, 0, v167, s[58:59]
	v_cndmask_b32_e64 v166, 0, v166, s[0:1]
	v_add_u32_e32 v164, v164, v166
	v_add_u32_e32 v166, v165, v167
	v_mov_b32_e32 v165, s76
	v_mov_b32_e32 v167, s74
	v_cndmask_b32_e64 v169, v165, v167, s[58:59]
	v_mov_b32_e32 v165, s75
	v_mov_b32_e32 v167, s73
	v_cndmask_b32_e64 v168, v165, v167, s[58:59]
	v_mov_b32_e32 v165, s71
	v_mov_b32_e32 v167, s37
	v_cndmask_b32_e64 v171, v165, v167, s[0:1]
	v_mov_b32_e32 v165, s70
	v_mov_b32_e32 v167, s28
	v_cndmask_b32_e64 v170, v165, v167, s[0:1]
	v_ashrrev_i32_e32 v165, 31, v164
	v_ashrrev_i32_e32 v167, 31, v166
	v_lshl_add_u64 v[164:165], v[164:165], 2, v[170:171]
	v_lshl_add_u64 v[166:167], v[166:167], 2, v[168:169]
	global_load_dword v240, v[164:165], off
	s_nop 0
	global_load_dword v241, v[166:167], off
	v_add_u32_e32 v116, -2, v116
	v_add_u32_e32 v242, 0xfffff800, v118
	v_cmp_eq_u32_e64 s[0:1], 0, v116
	v_add_u32_e32 v113, 0x400, v113
	v_add_u32_e32 v112, 0x400, v112
	s_or_b64 s[64:65], s[0:1], s[64:65]
	v_mov_b32_e32 v243, v118
	v_add_u32_e32 v118, 0x1000, v118
	s_andn2_b64 exec, exec, s[64:65]
	s_cbranch_execnz .LBB0_1130
	s_or_b64 exec, exec, s[64:65]
	s_orn2_b64 s[0:1], s[56:57], exec
	v_mov_b32_e32 v112, v154

; #define LDS_BARRIER() do { asm volatile("s_waitcnt lgkmcnt(0)" ::: "memory"); __builtin_amdgcn_s_barrier(); asm volatile("" ::: "memory"); } while (0)
; DI void ssd_cb_phase(const bf16_t* P, bf16_t* BT, bf16_t* Cc, bf16_t* CB, const float* dt, float* acs,
;                      const float* cw, const float* cb, const float* A_log, char* lds) {
;     ...
;     for (int q = tid; q < 1280; q += 512) { const int which = q / 640, r = q % 640, kk = r >> 7, col = 2048 + which * 512 + g * 128 + (r & 127); sW[q] = (kk < 4) ? cw[kk * 3072 + col] : cb[col]; }
;     LDS_BARRIER();
.LBB0_1134:
	v_mul_hi_i32 v116, v112, s39
	v_lshrrev_b32_e32 v118, 31, v116
	v_ashrrev_i32_e32 v116, 8, v116
	v_add_u32_e32 v116, v116, v118
	v_mul_i32_i24_e32 v118, 0x280, v116
	v_sub_u32_e32 v118, v112, v118
	v_ashrrev_i32_e32 v164, 7, v118
	v_lshl_add_u32 v116, v116, 9, s41
	v_and_or_b32 v116, v118, s79, v116
	v_cmp_gt_i32_e64 s[0:1], 4, v164
	v_mul_lo_u32 v118, v164, s91
	s_nop 0
	v_cndmask_b32_e64 v118, 0, v118, s[0:1]
	v_add_u32_e32 v164, v116, v118
	v_mov_b32_e32 v116, s71
	v_mov_b32_e32 v118, s37
	v_cndmask_b32_e64 v167, v116, v118, s[0:1]
	v_mov_b32_e32 v116, s70
	v_mov_b32_e32 v118, s28
	v_cndmask_b32_e64 v166, v116, v118, s[0:1]
	v_ashrrev_i32_e32 v165, 31, v164
	v_lshl_add_u64 v[164:165], v[164:165], 2, v[166:167]
	global_load_dword v244, v[164:165], off
	s_movk_i32 s0, 0x2ff
	v_cmp_lt_i32_e64 s[0:1], s0, v112
	s_or_b64 s[58:59], s[0:1], s[58:59]
	v_mov_b32_e32 v245, v113
	v_add_u32_e32 v116, 0x200, v112
	v_add_u32_e32 v113, 0x800, v113
	v_mov_b32_e32 v112, v116
	s_andn2_b64 exec, exec, s[58:59]
	s_cbranch_execnz .LBB0_1134
	s_branch .LBB0_1126
